# LRU gate GEMM: kk=2,3 B-fragment LDS reads issued with kk=0,1 (one exposed LDS latency per n-block); plus final norm, peel, epilogue fast paths, LRU prefetch, sc1
# baseline (speedup 1.0000x reference)
; #define LAS __attribute__((address_space(3)))
; __device__ __forceinline__ unsigned cvt_pk_bf16(float lo, float hi) { unsigned r; asm volatile("v_cvt_pk_bf16_f32 %0, %1, %2" : "=v"(r) : "v"(lo), "v"(hi)); return r; }
; __device__ __forceinline__ float bflo(unsigned w) { return __uint_as_float(w << 16); }
; __device__ __forceinline__ float bfhi(unsigned w) { return __uint_as_float(w & 0xffff0000u); }
; template <int PASS> __device__ __forceinline__ void lru_wave_item(LAS unsigned char* lds, LAS unsigned char* vw, int b, int c, int h, const MixP& p, int lane, float (&Hrun)[8], bool cont) {
;     ...
;     for (int st = 0; st < CT / 16; ++st) {
;         const int s0 = c * CT + 16 * st;
;         u32x4 ur[7];
;         {
;             const int sb = s0 + 4 * fq - 3;
; #pragma unroll
;             for (int r = 0; r < 7; ++r) ur[r] = *(const u32x4*)(ub + (size_t)max(sb + r, 0) * P1W);
;         }
;         if (s0 == 0 && fq == 0) {
; #pragma unroll
;             for (int r = 0; r < 3; ++r) ur[r] = (u32x4){0u, 0u, 0u, 0u};
;         }
; #pragma unroll
;         for (int jj = 0; jj < 4; ++jj) {
;             f32x2 o[4] = {bv[0], bv[1], bv[2], bv[3]};
; #pragma unroll
;             for (int k = 0; k < 4; ++k) { const u32x4 uk = ur[jj + k];
;                 o[0] = wv[k][0] * (f32x2){bflo(uk.x), bfhi(uk.x)} + o[0]; o[1] = wv[k][1] * (f32x2){bflo(uk.y), bfhi(uk.y)} + o[1];
;                 o[2] = wv[k][2] * (f32x2){bflo(uk.z), bfhi(uk.z)} + o[2]; o[3] = wv[k][3] * (f32x2){bflo(uk.w), bfhi(uk.w)} + o[3]; }
;             { u32x4 w; w.x = cvt_pk_bf16(o[0].x, o[0].y); w.y = cvt_pk_bf16(o[1].x, o[1].y); w.z = cvt_pk_bf16(o[2].x, o[2].y); w.w = cvt_pk_bf16(o[3].x, o[3].y);
;               *(LAS u32x4*)(vw + (4 * fq + jj) * WROW + cg * 16) = w; }
;         }
.LBB0_668:
	s_or_b32 s2, s19, s13
	v_add_u32_e32 v74, s2, v230
	v_cndmask_b32_e64 v50, 0, 1, s[28:29]
	v_max_i32_e32 v54, -1, v74
	v_cmp_ne_u32_e32 vcc, 1, v50
	v_max_i32_e32 v50, 0, v74
	v_add_u32_e32 v54, 1, v54
	v_or_b32_e32 v58, 2, v74
	v_mad_u64_u32 v[50:51], s[20:21], v50, s82, v[196:197]
	v_mad_u64_u32 v[54:55], s[20:21], v54, s82, v[196:197]
	v_max_i32_e32 v58, 0, v58
	global_load_dwordx4 v[50:53], v[50:51], off offset:1024
	v_mad_u64_u32 v[58:59], s[20:21], v58, s82, v[196:197]
	global_load_dwordx4 v[54:57], v[54:55], off offset:1024
	v_or_b32_e32 v62, s2, v229
	global_load_dwordx4 v[58:61], v[58:59], off offset:1024
	v_max_i32_e32 v62, 0, v62
	v_mad_u64_u32 v[62:63], s[20:21], v62, s82, v[196:197]
	global_load_dwordx4 v[62:65], v[62:63], off offset:1024
	v_max_i32_e32 v66, -4, v74
	v_add_u32_e32 v66, 4, v66
	v_mad_u64_u32 v[66:67], s[20:21], v66, s82, v[196:197]
	global_load_dwordx4 v[66:69], v[66:67], off offset:1024
	v_max_i32_e32 v70, -5, v74
	v_add_u32_e32 v70, 5, v70
	v_mad_u64_u32 v[70:71], s[20:21], v70, s82, v[196:197]
	global_load_dwordx4 v[70:73], v[70:71], off offset:1024
	v_max_i32_e32 v74, -6, v74
	v_add_u32_e32 v74, 6, v74
	v_mad_u64_u32 v[74:75], s[20:21], v74, s82, v[196:197]
	global_load_dwordx4 v[74:77], v[74:75], off offset:1024
	s_add_i32 s100, s2, 16
	v_add_u32_e32 v92, s100, v230
	v_max_i32_e32 v93, 0, v92
	v_mad_u64_u32 v[94:95], s[98:99], v93, s82, v[196:197]
	global_load_dword v206, v[94:95], off offset:1024
	v_add_u32_e32 v93, 1, v92
	v_max_i32_e32 v93, 0, v93
	v_mad_u64_u32 v[94:95], s[98:99], v93, s82, v[196:197]
	global_load_dword v206, v[94:95], off offset:1024
	v_add_u32_e32 v93, 2, v92
	v_max_i32_e32 v93, 0, v93
	v_mad_u64_u32 v[94:95], s[98:99], v93, s82, v[196:197]
	global_load_dword v206, v[94:95], off offset:1024
	v_add_u32_e32 v93, 3, v92
	v_max_i32_e32 v93, 0, v93
	v_mad_u64_u32 v[94:95], s[98:99], v93, s82, v[196:197]
	global_load_dword v206, v[94:95], off offset:1024
	v_add_u32_e32 v93, 4, v92
	v_max_i32_e32 v93, 0, v93
	v_mad_u64_u32 v[94:95], s[98:99], v93, s82, v[196:197]
	global_load_dword v206, v[94:95], off offset:1024
	v_add_u32_e32 v93, 5, v92
	v_max_i32_e32 v93, 0, v93
	v_mad_u64_u32 v[94:95], s[98:99], v93, s82, v[196:197]
	global_load_dword v206, v[94:95], off offset:1024
	v_add_u32_e32 v93, 6, v92
	v_max_i32_e32 v93, 0, v93
	v_mad_u64_u32 v[94:95], s[98:99], v93, s82, v[196:197]
	global_load_dword v206, v[94:95], off offset:1024
	s_cmp_eq_u32 s2, 0
	s_cselect_b64 s[16:17], -1, 0
	s_and_b64 s[16:17], s[16:17], s[4:5]
	v_add_u32_e32 v138, v234, v231
	s_mov_b32 s19, 16
	s_mov_b64 s[28:29], 0
	s_and_b64 vcc, exec, vcc
	s_waitcnt vmcnt(12)
	v_cndmask_b32_e64 v81, v57, 0, s[16:17]
	v_cndmask_b32_e64 v57, v53, 0, s[16:17]
	v_cndmask_b32_e64 v53, v51, 0, s[16:17]
	v_cndmask_b32_e64 v51, v50, 0, s[16:17]
	s_waitcnt vmcnt(11)
	v_cndmask_b32_e64 v85, v59, 0, s[16:17]
	v_cndmask_b32_e64 v59, v54, 0, s[16:17]
	v_lshlrev_b32_e32 v50, 16, v51
	v_and_b32_e32 v51, 0xffff0000, v51
	v_cndmask_b32_e64 v89, v61, 0, s[16:17]
	v_cndmask_b32_e64 v83, v58, 0, s[16:17]
	v_cndmask_b32_e64 v61, v55, 0, s[16:17]
	v_cndmask_b32_e64 v55, v52, 0, s[16:17]
	s_waitcnt lgkmcnt(13)
	v_pk_fma_f32 v[50:51], v[10:11], v[50:51], v[42:43]
	v_lshlrev_b32_e32 v52, 16, v53
	v_and_b32_e32 v53, 0xffff0000, v53
	v_lshlrev_b32_e32 v58, 16, v59
	v_and_b32_e32 v59, 0xffff0000, v59
	v_cndmask_b32_e64 v87, v60, 0, s[16:17]
	v_cndmask_b32_e64 v79, v56, 0, s[16:17]
	v_pk_fma_f32 v[52:53], v[12:13], v[52:53], v[44:45]
	v_lshlrev_b32_e32 v54, 16, v55
	v_and_b32_e32 v55, 0xffff0000, v55
	v_lshlrev_b32_e32 v56, 16, v57
	v_and_b32_e32 v57, 0xffff0000, v57
	v_pk_fma_f32 v[50:51], v[18:19], v[58:59], v[50:51]
	v_lshlrev_b32_e32 v60, 16, v61
	v_and_b32_e32 v61, 0xffff0000, v61
	v_lshlrev_b32_e32 v82, 16, v83
	v_and_b32_e32 v83, 0xffff0000, v83
	s_waitcnt lgkmcnt(12)
	v_pk_fma_f32 v[54:55], v[14:15], v[54:55], v[46:47]
	v_pk_fma_f32 v[56:57], v[16:17], v[56:57], v[48:49]
	v_pk_fma_f32 v[52:53], v[20:21], v[60:61], v[52:53]
	v_lshlrev_b32_e32 v78, 16, v79
	v_and_b32_e32 v79, 0xffff0000, v79
	v_lshlrev_b32_e32 v80, 16, v81
	v_and_b32_e32 v81, 0xffff0000, v81
	v_pk_fma_f32 v[50:51], v[26:27], v[82:83], v[50:51]
	v_lshlrev_b32_e32 v84, 16, v85
	v_and_b32_e32 v85, 0xffff0000, v85
	s_waitcnt vmcnt(10)
	v_lshlrev_b32_e32 v90, 16, v62
	v_and_b32_e32 v91, 0xffff0000, v62
	v_pk_fma_f32 v[54:55], v[22:23], v[78:79], v[54:55]
	v_pk_fma_f32 v[56:57], v[24:25], v[80:81], v[56:57]
	v_pk_fma_f32 v[52:53], v[28:29], v[84:85], v[52:53]
	v_lshlrev_b32_e32 v86, 16, v87
	v_and_b32_e32 v87, 0xffff0000, v87
	v_lshlrev_b32_e32 v88, 16, v89
	v_and_b32_e32 v89, 0xffff0000, v89
	v_pk_fma_f32 v[50:51], v[34:35], v[90:91], v[50:51]
	v_lshlrev_b32_e32 v62, 16, v63
	v_and_b32_e32 v63, 0xffff0000, v63
	v_pk_fma_f32 v[54:55], v[30:31], v[86:87], v[54:55]
	v_pk_fma_f32 v[56:57], v[32:33], v[88:89], v[56:57]
	v_pk_fma_f32 v[52:53], v[36:37], v[62:63], v[52:53]
	v_lshlrev_b32_e32 v92, 16, v64
	v_and_b32_e32 v93, 0xffff0000, v64
	v_lshlrev_b32_e32 v64, 16, v65
	v_and_b32_e32 v65, 0xffff0000, v65
	v_cvt_pk_bf16_f32 v50, v50, v51
	v_cvt_pk_bf16_f32 v51, v52, v53
	v_pk_fma_f32 v[54:55], v[38:39], v[92:93], v[54:55]
	v_pk_fma_f32 v[56:57], v[40:41], v[64:65], v[56:57]
	v_cvt_pk_bf16_f32 v52, v54, v55
	v_pk_fma_f32 v[54:55], v[14:15], v[78:79], v[46:47]
	v_cvt_pk_bf16_f32 v53, v56, v57
	ds_write_b128 v247, v[50:53]
	v_pk_fma_f32 v[50:51], v[10:11], v[58:59], v[42:43]
	v_pk_fma_f32 v[52:53], v[12:13], v[60:61], v[44:45]
	v_pk_fma_f32 v[50:51], v[18:19], v[82:83], v[50:51]
	v_pk_fma_f32 v[56:57], v[16:17], v[80:81], v[48:49]
	v_pk_fma_f32 v[52:53], v[20:21], v[84:85], v[52:53]
	v_pk_fma_f32 v[50:51], v[26:27], v[90:91], v[50:51]
	s_waitcnt vmcnt(9)
; #define LAS __attribute__((address_space(3)))
; __device__ __forceinline__ unsigned cvt_pk_bf16(float lo, float hi) { unsigned r; asm volatile("v_cvt_pk_bf16_f32 %0, %1, %2" : "=v"(r) : "v"(lo), "v"(hi)); return r; }
; __device__ __forceinline__ float bflo(unsigned w) { return __uint_as_float(w << 16); }
; __device__ __forceinline__ float bfhi(unsigned w) { return __uint_as_float(w & 0xffff0000u); }
; template <int PASS> __device__ __forceinline__ void lru_wave_item(LAS unsigned char* lds, LAS unsigned char* vw, int b, int c, int h, const MixP& p, int lane, float (&Hrun)[8], bool cont) {
;     ...
;             for (int k = 0; k < 4; ++k) { const u32x4 uk = ur[jj + k];
;                 o[0] = wv[k][0] * (f32x2){bflo(uk.x), bfhi(uk.x)} + o[0]; o[1] = wv[k][1] * (f32x2){bflo(uk.y), bfhi(uk.y)} + o[1];
;                 o[2] = wv[k][2] * (f32x2){bflo(uk.z), bfhi(uk.z)} + o[2]; o[3] = wv[k][3] * (f32x2){bflo(uk.w), bfhi(uk.w)} + o[3]; }
;             { u32x4 w; w.x = cvt_pk_bf16(o[0].x, o[0].y); w.y = cvt_pk_bf16(o[1].x, o[1].y); w.z = cvt_pk_bf16(o[2].x, o[2].y); w.w = cvt_pk_bf16(o[3].x, o[3].y);
;               *(LAS u32x4*)(vw + (4 * fq + jj) * WROW + cg * 16) = w; }
;         }
;         f32x4 aR[8], aI[8];
;         bf16x8 af[4];
;         {
; #pragma unroll
;             for (int kk = 0; kk < 4; ++kk) af[kk] = *(const LAS bf16x8*)(vw + fr * WROW + kk * 64 + fq * 16);
; #pragma unroll
;             for (int n = 0; n < 8; ++n) {
;                 aR[n] = (f32x4){0.f, 0.f, 0.f, 0.f}; aI[n] = (f32x4){0.f, 0.f, 0.f, 0.f};
; #pragma unroll
;                 for (int kk = 0; kk < 4; ++kk) {
;                     const bf16x8 ba = *(const LAS bf16x8*)(lds + WA_OFF + (16 * n + fr) * WROW + kk * 64 + fq * 16);
;                     const bf16x8 bx = *(const LAS bf16x8*)(lds + WX_OFF + (16 * n + fr) * WROW + kk * 64 + fq * 16);
;                     aR[n] = __builtin_amdgcn_mfma_f32_16x16x32_bf16(af[kk], ba, aR[n], 0, 0, 0);
;                     aI[n] = __builtin_amdgcn_mfma_f32_16x16x32_bf16(af[kk], bx, aI[n], 0, 0, 0);
;                 }
;             }
	v_lshlrev_b32_e32 v58, 16, v66
	v_and_b32_e32 v59, 0xffff0000, v66
	v_pk_fma_f32 v[54:55], v[22:23], v[86:87], v[54:55]
	v_pk_fma_f32 v[56:57], v[24:25], v[88:89], v[56:57]
	v_pk_fma_f32 v[52:53], v[28:29], v[62:63], v[52:53]
	v_pk_fma_f32 v[50:51], v[34:35], v[58:59], v[50:51]
	v_lshlrev_b32_e32 v60, 16, v67
	v_and_b32_e32 v61, 0xffff0000, v67
	v_pk_fma_f32 v[54:55], v[30:31], v[92:93], v[54:55]
	v_pk_fma_f32 v[56:57], v[32:33], v[64:65], v[56:57]
	v_pk_fma_f32 v[52:53], v[36:37], v[60:61], v[52:53]
	v_lshlrev_b32_e32 v66, 16, v68
	v_and_b32_e32 v67, 0xffff0000, v68
	v_lshlrev_b32_e32 v68, 16, v69
	v_and_b32_e32 v69, 0xffff0000, v69
	v_cvt_pk_bf16_f32 v50, v50, v51
	v_cvt_pk_bf16_f32 v51, v52, v53
	v_pk_fma_f32 v[54:55], v[38:39], v[66:67], v[54:55]
	v_pk_fma_f32 v[56:57], v[40:41], v[68:69], v[56:57]
	v_cvt_pk_bf16_f32 v52, v54, v55
	v_pk_fma_f32 v[54:55], v[14:15], v[86:87], v[46:47]
	v_cvt_pk_bf16_f32 v53, v56, v57
	ds_write_b128 v247, v[50:53] offset:272
	v_pk_fma_f32 v[50:51], v[10:11], v[82:83], v[42:43]
	v_pk_fma_f32 v[52:53], v[12:13], v[84:85], v[44:45]
	v_pk_fma_f32 v[50:51], v[18:19], v[90:91], v[50:51]
	v_pk_fma_f32 v[56:57], v[16:17], v[88:89], v[48:49]
	v_pk_fma_f32 v[52:53], v[20:21], v[62:63], v[52:53]
	v_pk_fma_f32 v[50:51], v[26:27], v[58:59], v[50:51]
	s_waitcnt vmcnt(8)
	v_lshlrev_b32_e32 v78, 16, v70
	v_and_b32_e32 v79, 0xffff0000, v70
	v_pk_fma_f32 v[54:55], v[22:23], v[92:93], v[54:55]
	v_pk_fma_f32 v[56:57], v[24:25], v[64:65], v[56:57]
	v_pk_fma_f32 v[52:53], v[28:29], v[60:61], v[52:53]
	v_pk_fma_f32 v[50:51], v[34:35], v[78:79], v[50:51]
	v_lshlrev_b32_e32 v70, 16, v71
	v_and_b32_e32 v71, 0xffff0000, v71
	v_pk_fma_f32 v[54:55], v[30:31], v[66:67], v[54:55]
	v_pk_fma_f32 v[56:57], v[32:33], v[68:69], v[56:57]
	v_pk_fma_f32 v[52:53], v[36:37], v[70:71], v[52:53]
	v_lshlrev_b32_e32 v80, 16, v72
	v_and_b32_e32 v81, 0xffff0000, v72
	v_lshlrev_b32_e32 v72, 16, v73
	v_and_b32_e32 v73, 0xffff0000, v73
	v_cvt_pk_bf16_f32 v50, v50, v51
	v_cvt_pk_bf16_f32 v51, v52, v53
	v_pk_fma_f32 v[54:55], v[38:39], v[80:81], v[54:55]
	v_pk_fma_f32 v[56:57], v[40:41], v[72:73], v[56:57]
	v_cvt_pk_bf16_f32 v52, v54, v55
	v_pk_fma_f32 v[54:55], v[14:15], v[92:93], v[46:47]
	v_cvt_pk_bf16_f32 v53, v56, v57
	ds_write_b128 v247, v[50:53] offset:544
	v_pk_fma_f32 v[50:51], v[10:11], v[90:91], v[42:43]
	v_pk_fma_f32 v[52:53], v[12:13], v[62:63], v[44:45]
	v_pk_fma_f32 v[50:51], v[18:19], v[58:59], v[50:51]
	v_pk_fma_f32 v[52:53], v[20:21], v[60:61], v[52:53]
	v_pk_fma_f32 v[50:51], v[26:27], v[78:79], v[50:51]
	s_waitcnt vmcnt(7)
	v_lshlrev_b32_e32 v58, 16, v74
	v_and_b32_e32 v59, 0xffff0000, v74
	v_pk_fma_f32 v[56:57], v[16:17], v[64:65], v[48:49]
	v_pk_fma_f32 v[54:55], v[22:23], v[66:67], v[54:55]
	v_pk_fma_f32 v[52:53], v[28:29], v[70:71], v[52:53]
	v_pk_fma_f32 v[50:51], v[34:35], v[58:59], v[50:51]
	v_lshlrev_b32_e32 v58, 16, v75
	v_and_b32_e32 v59, 0xffff0000, v75
	v_pk_fma_f32 v[56:57], v[24:25], v[68:69], v[56:57]
	v_pk_fma_f32 v[54:55], v[30:31], v[80:81], v[54:55]
	v_pk_fma_f32 v[52:53], v[36:37], v[58:59], v[52:53]
	v_lshlrev_b32_e32 v58, 16, v76
	v_and_b32_e32 v59, 0xffff0000, v76
	v_pk_fma_f32 v[56:57], v[32:33], v[72:73], v[56:57]
	v_pk_fma_f32 v[54:55], v[38:39], v[58:59], v[54:55]
	v_lshlrev_b32_e32 v58, 16, v77
	v_and_b32_e32 v59, 0xffff0000, v77
	v_cvt_pk_bf16_f32 v50, v50, v51
	v_pk_fma_f32 v[56:57], v[40:41], v[58:59], v[56:57]
	v_cvt_pk_bf16_f32 v51, v52, v53
	v_cvt_pk_bf16_f32 v52, v54, v55
	v_add_u32_e32 v74, v234, v235
	v_cvt_pk_bf16_f32 v53, v56, v57
	ds_write_b128 v247, v[50:53] offset:816
	v_add_u32_e32 v50, v232, v233
	ds_read_b128 v[110:113], v50
	ds_read_b128 v[82:85], v50 offset:64
	ds_read_b128 v[54:57], v50 offset:128
	ds_read_b128 v[50:53], v50 offset:192
	ds_read_b128 v[58:61], v138
	ds_read_b128 v[62:65], v138 offset:34816
	ds_read_b128 v[66:69], v138 offset:64
	ds_read_b128 v[70:73], v138 offset:34880
	ds_read_b128 v[94:97], v138 offset:128
	ds_read_b128 v[98:101], v138 offset:34944
	ds_read_b128 v[198:201], v138 offset:192
	ds_read_b128 v[202:205], v138 offset:35008
	s_waitcnt lgkmcnt(7)
	v_mfma_f32_16x16x32_bf16 v[58:61], v[110:113], v[58:61], 0
	s_waitcnt lgkmcnt(6)
	v_mfma_f32_16x16x32_bf16 v[62:65], v[110:113], v[62:65], 0
	s_waitcnt lgkmcnt(5)
	v_mfma_f32_16x16x32_bf16 v[58:61], v[82:85], v[66:69], v[58:61]
	s_waitcnt lgkmcnt(4)
	v_mfma_f32_16x16x32_bf16 v[62:65], v[82:85], v[70:73], v[62:65]
	s_waitcnt lgkmcnt(3)
	v_mfma_f32_16x16x32_bf16 v[58:61], v[54:57], v[94:97], v[58:61]
	s_waitcnt lgkmcnt(2)
	v_mfma_f32_16x16x32_bf16 v[62:65], v[54:57], v[98:101], v[62:65]
	s_waitcnt lgkmcnt(1)
	v_mfma_f32_16x16x32_bf16 v[126:129], v[50:53], v[198:201], v[58:61]
	s_waitcnt lgkmcnt(0)
	v_mfma_f32_16x16x32_bf16 v[122:125], v[50:53], v[202:205], v[62:65]
	s_nop 0
	ds_read_b128 v[58:61], v138 offset:4352
	s_nop 0
	ds_read_b128 v[62:65], v138 offset:39168
	ds_read_b128 v[66:69], v138 offset:4416
	ds_read_b128 v[70:73], v138 offset:39232
	ds_read_b128 v[94:97], v138 offset:4480
	ds_read_b128 v[98:101], v138 offset:39296
	ds_read_b128 v[198:201], v138 offset:4544
	ds_read_b128 v[202:205], v138 offset:39360
	v_add_f32_e32 v126, v170, v126
	s_waitcnt lgkmcnt(7)
	v_mfma_f32_16x16x32_bf16 v[58:61], v[110:113], v[58:61], 0
	v_add_f32_e32 v127, v170, v127
	v_mul_f32_e32 v126, 0xbfb8aa3b, v126
	v_mul_f32_e32 v127, 0xbfb8aa3b, v127
	s_waitcnt lgkmcnt(6)
	v_mfma_f32_16x16x32_bf16 v[62:65], v[110:113], v[62:65], 0
	v_exp_f32_e32 v126, v126
	v_exp_f32_e32 v127, v127
	v_add_f32_e32 v122, v174, v122
	s_waitcnt lgkmcnt(5)
	v_mfma_f32_16x16x32_bf16 v[58:61], v[82:85], v[66:69], v[58:61]
	v_add_f32_e32 v126, 1.0, v126
	v_add_f32_e32 v127, 1.0, v127
	v_rcp_f32_e32 v126, v126
	s_waitcnt lgkmcnt(4)
; #define LAS __attribute__((address_space(3)))
; template <int PASS> __device__ __forceinline__ void lru_wave_item(LAS unsigned char* lds, LAS unsigned char* vw, int b, int c, int h, const MixP& p, int lane, float (&Hrun)[8], bool cont) {
;     ...
;         {
; #pragma unroll
;             for (int kk = 0; kk < 4; ++kk) af[kk] = *(const LAS bf16x8*)(vw + fr * WROW + kk * 64 + fq * 16);
; #pragma unroll
;             for (int n = 0; n < 8; ++n) {
;                 aR[n] = (f32x4){0.f, 0.f, 0.f, 0.f}; aI[n] = (f32x4){0.f, 0.f, 0.f, 0.f};
; #pragma unroll
;                 for (int kk = 0; kk < 4; ++kk) {
;                     const bf16x8 ba = *(const LAS bf16x8*)(lds + WA_OFF + (16 * n + fr) * WROW + kk * 64 + fq * 16);
;                     const bf16x8 bx = *(const LAS bf16x8*)(lds + WX_OFF + (16 * n + fr) * WROW + kk * 64 + fq * 16);
;                     aR[n] = __builtin_amdgcn_mfma_f32_16x16x32_bf16(af[kk], ba, aR[n], 0, 0, 0);
;                     aI[n] = __builtin_amdgcn_mfma_f32_16x16x32_bf16(af[kk], bx, aI[n], 0, 0, 0);
;                 }
;             }
	v_mfma_f32_16x16x32_bf16 v[62:65], v[82:85], v[70:73], v[62:65]
	v_rcp_f32_e32 v127, v127
	v_mul_f32_e32 v126, v176, v126
	s_waitcnt lgkmcnt(3)
	v_mfma_f32_16x16x32_bf16 v[58:61], v[54:57], v[94:97], v[58:61]
	v_add_f32_e32 v123, v174, v123
	v_mul_f32_e32 v127, v176, v127
	v_mul_f32_e32 v122, 0xbfb8aa3b, v122
	s_waitcnt lgkmcnt(2)
	v_mfma_f32_16x16x32_bf16 v[62:65], v[54:57], v[98:101], v[62:65]
	v_mul_f32_e32 v123, 0xbfb8aa3b, v123
	v_exp_f32_e32 v122, v122
	s_waitcnt lgkmcnt(1)
	v_mfma_f32_16x16x32_bf16 v[118:121], v[50:53], v[198:201], v[58:61]
	v_exp_f32_e32 v123, v123
	v_add_f32_e32 v122, 1.0, v122
	v_rcp_f32_e32 v122, v122
	s_waitcnt lgkmcnt(0)
	v_mfma_f32_16x16x32_bf16 v[114:117], v[50:53], v[202:205], v[62:65]
	ds_read_b128 v[58:61], v138 offset:8704
	s_nop 1
	ds_read_b128 v[62:65], v138 offset:43520
	ds_read_b128 v[66:69], v138 offset:8768
	ds_read_b128 v[70:73], v138 offset:43584
	ds_read_b128 v[94:97], v138 offset:8832
	ds_read_b128 v[98:101], v138 offset:43648
	ds_read_b128 v[198:201], v138 offset:8896
	ds_read_b128 v[202:205], v138 offset:43712
	v_add_f32_e32 v123, 1.0, v123
	s_waitcnt lgkmcnt(7)
	v_mfma_f32_16x16x32_bf16 v[58:61], v[110:113], v[58:61], 0
	v_rcp_f32_e32 v123, v123
	v_add_f32_e32 v124, v174, v124
	v_add_f32_e32 v125, v174, v125
	s_waitcnt lgkmcnt(6)
	v_mfma_f32_16x16x32_bf16 v[62:65], v[110:113], v[62:65], 0
	v_mul_f32_e32 v124, 0xbfb8aa3b, v124
	v_mul_f32_e32 v125, 0xbfb8aa3b, v125
	v_exp_f32_e32 v124, v124
	s_waitcnt lgkmcnt(5)
	v_mfma_f32_16x16x32_bf16 v[58:61], v[82:85], v[66:69], v[58:61]
	v_exp_f32_e32 v125, v125
	v_add_f32_e32 v118, v171, v118
	v_add_f32_e32 v119, v171, v119
	s_waitcnt lgkmcnt(4)
	v_mfma_f32_16x16x32_bf16 v[62:65], v[82:85], v[70:73], v[62:65]
	v_add_f32_e32 v124, 1.0, v124
	v_add_f32_e32 v125, 1.0, v125
	s_waitcnt lgkmcnt(3)
	v_mfma_f32_16x16x32_bf16 v[58:61], v[54:57], v[94:97], v[58:61]
	v_mul_f32_e32 v118, 0xbfb8aa3b, v118
	v_mul_f32_e32 v119, 0xbfb8aa3b, v119
	v_rcp_f32_e32 v124, v124
	s_waitcnt lgkmcnt(2)
	v_mfma_f32_16x16x32_bf16 v[62:65], v[54:57], v[98:101], v[62:65]
	v_exp_f32_e32 v118, v118
	v_exp_f32_e32 v119, v119
	s_waitcnt lgkmcnt(1)
	v_mfma_f32_16x16x32_bf16 v[106:109], v[50:53], v[198:201], v[58:61]
	v_add_f32_e32 v118, 1.0, v118
	v_add_f32_e32 v119, 1.0, v119
	v_rcp_f32_e32 v118, v118
	s_waitcnt lgkmcnt(0)
	v_mfma_f32_16x16x32_bf16 v[102:105], v[50:53], v[202:205], v[62:65]
	ds_read_b128 v[58:61], v74
	s_nop 1
	ds_read_b128 v[62:65], v74 offset:34816
	ds_read_b128 v[66:69], v74 offset:64
	ds_read_b128 v[70:73], v74 offset:34880
	ds_read_b128 v[94:97], v74 offset:128
	ds_read_b128 v[98:101], v74 offset:34944
	ds_read_b128 v[198:201], v74 offset:192
	ds_read_b128 v[202:205], v74 offset:35008
	v_rcp_f32_e32 v119, v119
	s_waitcnt lgkmcnt(7)
	v_mfma_f32_16x16x32_bf16 v[58:61], v[110:113], v[58:61], 0
	v_add_f32_e32 v114, v175, v114
	v_mul_f32_e32 v118, v177, v118
	v_add_f32_e32 v115, v175, v115
	s_waitcnt lgkmcnt(6)
	v_mfma_f32_16x16x32_bf16 v[62:65], v[110:113], v[62:65], 0
	v_mul_f32_e32 v119, v177, v119
	v_mul_f32_e32 v114, 0xbfb8aa3b, v114
	v_mul_f32_e32 v115, 0xbfb8aa3b, v115
	s_waitcnt lgkmcnt(5)
	v_mfma_f32_16x16x32_bf16 v[58:61], v[82:85], v[66:69], v[58:61]
	v_exp_f32_e32 v114, v114
	v_exp_f32_e32 v115, v115
	v_add_f32_e32 v106, v178, v106
	s_waitcnt lgkmcnt(4)
	v_mfma_f32_16x16x32_bf16 v[62:65], v[82:85], v[70:73], v[62:65]
	v_add_f32_e32 v114, 1.0, v114
	v_add_f32_e32 v115, 1.0, v115
	s_waitcnt lgkmcnt(3)
	v_mfma_f32_16x16x32_bf16 v[58:61], v[54:57], v[94:97], v[58:61]
	v_rcp_f32_e32 v114, v114
	v_rcp_f32_e32 v115, v115
	v_add_f32_e32 v107, v178, v107
	s_waitcnt lgkmcnt(2)
	v_mfma_f32_16x16x32_bf16 v[62:65], v[54:57], v[98:101], v[62:65]
	v_mul_f32_e32 v106, 0xbfb8aa3b, v106
	v_mul_f32_e32 v107, 0xbfb8aa3b, v107
	s_waitcnt lgkmcnt(1)
	v_mfma_f32_16x16x32_bf16 v[90:93], v[50:53], v[198:201], v[58:61]
	v_exp_f32_e32 v106, v106
	v_exp_f32_e32 v107, v107
	v_add_f32_e32 v102, v180, v102
	s_waitcnt lgkmcnt(0)
	v_mfma_f32_16x16x32_bf16 v[86:89], v[50:53], v[202:205], v[62:65]
	ds_read_b128 v[58:61], v138 offset:17408
	s_nop 1
	ds_read_b128 v[62:65], v138 offset:52224
	ds_read_b128 v[66:69], v138 offset:17472
	ds_read_b128 v[70:73], v138 offset:52288
	ds_read_b128 v[94:97], v138 offset:17536
	ds_read_b128 v[98:101], v138 offset:52352
	ds_read_b128 v[198:201], v138 offset:17600
	ds_read_b128 v[202:205], v138 offset:52416
	v_add_f32_e32 v106, 1.0, v106
	s_waitcnt lgkmcnt(7)
	v_mfma_f32_16x16x32_bf16 v[58:61], v[110:113], v[58:61], 0
	v_add_f32_e32 v107, 1.0, v107
	v_rcp_f32_e32 v106, v106
	v_rcp_f32_e32 v107, v107
	s_waitcnt lgkmcnt(6)
	v_mfma_f32_16x16x32_bf16 v[62:65], v[110:113], v[62:65], 0
	v_add_f32_e32 v103, v180, v103
	v_mul_f32_e32 v106, v182, v106
	v_mul_f32_e32 v107, v182, v107
	s_waitcnt lgkmcnt(5)
	v_mfma_f32_16x16x32_bf16 v[58:61], v[82:85], v[66:69], v[58:61]
	v_mul_f32_e32 v102, 0xbfb8aa3b, v102
	v_mul_f32_e32 v103, 0xbfb8aa3b, v103
	v_exp_f32_e32 v102, v102
	s_waitcnt lgkmcnt(4)
	v_mfma_f32_16x16x32_bf16 v[62:65], v[82:85], v[70:73], v[62:65]
	v_exp_f32_e32 v103, v103
	v_add_f32_e32 v102, 1.0, v102
	s_waitcnt lgkmcnt(3)
	v_mfma_f32_16x16x32_bf16 v[58:61], v[54:57], v[94:97], v[58:61]
	v_add_f32_e32 v103, 1.0, v103
	v_rcp_f32_e32 v102, v102
	v_rcp_f32_e32 v103, v103
	s_waitcnt lgkmcnt(2)
	v_mfma_f32_16x16x32_bf16 v[62:65], v[54:57], v[98:101], v[62:65]
	v_add_f32_e32 v104, v180, v104
	v_add_f32_e32 v105, v180, v105
	s_waitcnt lgkmcnt(1)
	v_mfma_f32_16x16x32_bf16 v[78:81], v[50:53], v[198:201], v[58:61]
	v_mul_f32_e32 v104, 0xbfb8aa3b, v104
	v_mul_f32_e32 v105, 0xbfb8aa3b, v105
	v_exp_f32_e32 v104, v104
	s_waitcnt lgkmcnt(0)
; #define LAS __attribute__((address_space(3)))
; __device__ __forceinline__ float fsig2(float x) { return __builtin_amdgcn_rcpf(1.0f + __builtin_amdgcn_exp2f(-LOG2E * x)); }
; template <int PASS> __device__ __forceinline__ void lru_wave_item(LAS unsigned char* lds, LAS unsigned char* vw, int b, int c, int h, const MixP& p, int lane, float (&Hrun)[8], bool cont) {
;     ...
;         {
; #pragma unroll
;             for (int kk = 0; kk < 4; ++kk) af[kk] = *(const LAS bf16x8*)(vw + fr * WROW + kk * 64 + fq * 16);
; #pragma unroll
;             for (int n = 0; n < 8; ++n) {
;                 aR[n] = (f32x4){0.f, 0.f, 0.f, 0.f}; aI[n] = (f32x4){0.f, 0.f, 0.f, 0.f};
; #pragma unroll
;                 for (int kk = 0; kk < 4; ++kk) {
;                     const bf16x8 ba = *(const LAS bf16x8*)(lds + WA_OFF + (16 * n + fr) * WROW + kk * 64 + fq * 16);
;                     const bf16x8 bx = *(const LAS bf16x8*)(lds + WX_OFF + (16 * n + fr) * WROW + kk * 64 + fq * 16);
;                     aR[n] = __builtin_amdgcn_mfma_f32_16x16x32_bf16(af[kk], ba, aR[n], 0, 0, 0);
;                     aI[n] = __builtin_amdgcn_mfma_f32_16x16x32_bf16(af[kk], bx, aI[n], 0, 0, 0);
;                 }
;             }
;         }
; #pragma unroll
;         for (int n = 0; n < 8; ++n) {
;             const f32x4 aVn = __builtin_amdgcn_mfma_f32_16x16x32_bf16(af[n >> 1], idf[n & 1], (f32x4){0.f, 0.f, 0.f, 0.f}, 0, 0, 0);
;             float av[4], bxv[4];
; #pragma unroll
;             for (int j = 0; j < 4; ++j) {
;                 const float r = fsig2(aR[n][j] + pba[n]), ig = fsig2(aI[n][j] + pbx[n]);
;                 const float a = __builtin_amdgcn_exp2f(r * pk8[n]), mult = __builtin_amdgcn_sqrtf(fmaxf(1.0f - a * a, 0.f));
	v_mfma_f32_16x16x32_bf16 v[74:77], v[50:53], v[202:205], v[62:65]
	ds_read_b128 v[58:61], v138 offset:21760
	s_nop 1
	ds_read_b128 v[62:65], v138 offset:56576
	ds_read_b128 v[66:69], v138 offset:21824
	ds_read_b128 v[70:73], v138 offset:56640
	v_exp_f32_e32 v105, v105
	s_waitcnt lgkmcnt(3)
	v_mfma_f32_16x16x32_bf16 v[58:61], v[110:113], v[58:61], 0
	v_add_f32_e32 v104, 1.0, v104
	v_add_f32_e32 v105, 1.0, v105
	v_rcp_f32_e32 v104, v104
	s_waitcnt lgkmcnt(2)
	v_mfma_f32_16x16x32_bf16 v[62:65], v[110:113], v[62:65], 0
	v_add_f32_e32 v90, v179, v90
	v_add_f32_e32 v91, v179, v91
	v_mul_f32_e32 v90, 0xbfb8aa3b, v90
	s_waitcnt lgkmcnt(1)
	v_mfma_f32_16x16x32_bf16 v[58:61], v[82:85], v[66:69], v[58:61]
	v_mul_f32_e32 v91, 0xbfb8aa3b, v91
	v_exp_f32_e32 v90, v90
	v_exp_f32_e32 v91, v91
	s_waitcnt lgkmcnt(0)
	v_mfma_f32_16x16x32_bf16 v[62:65], v[82:85], v[70:73], v[62:65]
	ds_read_b128 v[66:69], v138 offset:21888
	ds_read_b128 v[70:73], v138 offset:56704
	v_add_f32_e32 v90, 1.0, v90
	v_add_f32_e32 v91, 1.0, v91
	s_waitcnt lgkmcnt(1)
	v_mfma_f32_16x16x32_bf16 v[58:61], v[54:57], v[66:69], v[58:61]
	ds_read_b128 v[66:69], v138 offset:21952
	ds_read_b128 v[94:97], v138 offset:56768
	v_rcp_f32_e32 v90, v90
	v_rcp_f32_e32 v91, v91
	s_waitcnt lgkmcnt(2)
	v_mfma_f32_16x16x32_bf16 v[62:65], v[54:57], v[70:73], v[62:65]
	v_add_f32_e32 v86, v181, v86
	v_mul_f32_e32 v90, v183, v90
	v_add_f32_e32 v87, v181, v87
	s_waitcnt lgkmcnt(1)
	v_mfma_f32_16x16x32_bf16 v[70:73], v[50:53], v[66:69], v[58:61]
	v_mul_f32_e32 v91, v183, v91
	v_mul_f32_e32 v86, 0xbfb8aa3b, v86
	v_mul_f32_e32 v87, 0xbfb8aa3b, v87
	s_waitcnt lgkmcnt(0)
	v_mfma_f32_16x16x32_bf16 v[66:69], v[50:53], v[94:97], v[62:65]
	ds_read_b128 v[58:61], v138 offset:26112
	s_nop 1
	ds_read_b128 v[62:65], v138 offset:60928
	ds_read_b128 v[94:97], v138 offset:26176
	ds_read_b128 v[98:101], v138 offset:60992
	v_exp_f32_e32 v86, v86
	s_waitcnt lgkmcnt(3)
	v_mfma_f32_16x16x32_bf16 v[58:61], v[110:113], v[58:61], 0
	v_exp_f32_e32 v87, v87
	v_add_f32_e32 v86, 1.0, v86
	v_rcp_f32_e32 v86, v86
	s_waitcnt lgkmcnt(2)
	v_mfma_f32_16x16x32_bf16 v[62:65], v[110:113], v[62:65], 0
	v_add_f32_e32 v87, 1.0, v87
	v_rcp_f32_e32 v87, v87
	v_add_f32_e32 v78, v184, v78
	s_waitcnt lgkmcnt(1)
	v_mfma_f32_16x16x32_bf16 v[58:61], v[82:85], v[94:97], v[58:61]
	v_add_f32_e32 v79, v184, v79
	v_mul_f32_e32 v78, 0xbfb8aa3b, v78
	v_mul_f32_e32 v79, 0xbfb8aa3b, v79
	s_waitcnt lgkmcnt(0)
	v_mfma_f32_16x16x32_bf16 v[62:65], v[82:85], v[98:101], v[62:65]
	ds_read_b128 v[94:97], v138 offset:26240
	ds_read_b128 v[98:101], v138 offset:61056
	v_exp_f32_e32 v78, v78
	v_exp_f32_e32 v79, v79
	s_waitcnt lgkmcnt(1)
	v_mfma_f32_16x16x32_bf16 v[58:61], v[54:57], v[94:97], v[58:61]
	v_add_f32_e32 v78, 1.0, v78
	v_add_f32_e32 v79, 1.0, v79
	v_rcp_f32_e32 v78, v78
	s_waitcnt lgkmcnt(0)
	v_mfma_f32_16x16x32_bf16 v[94:97], v[54:57], v[98:101], v[62:65]
	s_nop 2
	ds_read_b128 v[62:65], v138 offset:26304
	ds_read_b128 v[98:101], v138 offset:61120
	v_rcp_f32_e32 v79, v79
	v_add_f32_e32 v74, v186, v74
	s_waitcnt lgkmcnt(1)
	v_mfma_f32_16x16x32_bf16 v[62:65], v[50:53], v[62:65], v[58:61]
	v_mul_f32_e32 v78, v188, v78
	v_add_f32_e32 v75, v186, v75
	v_mul_f32_e32 v79, v188, v79
	s_waitcnt lgkmcnt(0)
	v_mfma_f32_16x16x32_bf16 v[58:61], v[50:53], v[98:101], v[94:97]
	v_mul_f32_e32 v74, 0xbfb8aa3b, v74
	v_mul_f32_e32 v75, 0xbfb8aa3b, v75
	v_exp_f32_e32 v74, v74
	v_add_u32_e32 v94, v234, v236
	ds_read_b128 v[96:99], v94
	ds_read_b128 v[198:201], v94 offset:34816
	ds_read_b128 v[202:205], v94 offset:64
	ds_read_b128 v[138:141], v94 offset:34880
	s_waitcnt lgkmcnt(3)
	v_mfma_f32_16x16x32_bf16 v[96:99], v[110:113], v[96:99], 0
	v_exp_f32_e32 v75, v75
	v_add_f32_e32 v74, 1.0, v74
	v_rcp_f32_e32 v74, v74
	s_waitcnt lgkmcnt(2)
	v_mfma_f32_16x16x32_bf16 v[198:201], v[110:113], v[198:201], 0
	v_add_f32_e32 v75, 1.0, v75
	v_rcp_f32_e32 v75, v75
	v_add_f32_e32 v76, v186, v76
	s_waitcnt lgkmcnt(1)
	v_mfma_f32_16x16x32_bf16 v[96:99], v[82:85], v[202:205], v[96:99]
	v_add_f32_e32 v77, v186, v77
	v_mul_f32_e32 v76, 0xbfb8aa3b, v76
	v_mul_f32_e32 v77, 0xbfb8aa3b, v77
	s_waitcnt lgkmcnt(0)
	v_mfma_f32_16x16x32_bf16 v[138:141], v[82:85], v[138:141], v[198:201]
	s_nop 2
	ds_read_b128 v[198:201], v94 offset:128
	ds_read_b128 v[202:205], v94 offset:34944
	v_exp_f32_e32 v76, v76
	v_exp_f32_e32 v77, v77
	s_waitcnt lgkmcnt(1)
	v_mfma_f32_16x16x32_bf16 v[96:99], v[54:57], v[198:201], v[96:99]
	v_add_f32_e32 v76, 1.0, v76
	v_add_f32_e32 v77, 1.0, v77
	v_rcp_f32_e32 v76, v76
	s_waitcnt lgkmcnt(0)
	v_mfma_f32_16x16x32_bf16 v[138:141], v[54:57], v[202:205], v[138:141]
	ds_read_b128 v[198:201], v94 offset:192
	ds_read_b128 v[202:205], v94 offset:35008
	v_add_f32_e32 v70, v185, v70
	v_add_f32_e32 v71, v185, v71
	s_waitcnt lgkmcnt(1)
	v_mfma_f32_16x16x32_bf16 v[98:101], v[50:53], v[198:201], v[96:99]
	v_exp_f32_e32 v198, v126
	v_exp_f32_e32 v199, v127
	v_mul_f32_e32 v70, 0xbfb8aa3b, v70
	s_waitcnt lgkmcnt(0)
; __device__ __forceinline__ float fsig2(float x) { return __builtin_amdgcn_rcpf(1.0f + __builtin_amdgcn_exp2f(-LOG2E * x)); }
; template <int PASS> __device__ __forceinline__ void lru_wave_item(LAS unsigned char* lds, LAS unsigned char* vw, int b, int c, int h, const MixP& p, int lane, float (&Hrun)[8], bool cont) {
;     ...
;         for (int n = 0; n < 8; ++n) {
;             const f32x4 aVn = __builtin_amdgcn_mfma_f32_16x16x32_bf16(af[n >> 1], idf[n & 1], (f32x4){0.f, 0.f, 0.f, 0.f}, 0, 0, 0);
;             float av[4], bxv[4];
; #pragma unroll
;             for (int j = 0; j < 4; ++j) {
;                 const float r = fsig2(aR[n][j] + pba[n]), ig = fsig2(aI[n][j] + pbx[n]);
;                 const float a = __builtin_amdgcn_exp2f(r * pk8[n]), mult = __builtin_amdgcn_sqrtf(fmaxf(1.0f - a * a, 0.f));
;                 av[j] = a; bxv[j] = mult * ig * aVn[j];
;             }
;             const float H0 = bxv[0], H1 = av[1] * H0 + bxv[1], H2 = av[2] * H1 + bxv[2], H3 = av[3] * H2 + bxv[3];
;             const float A0 = av[0], A1 = av[1] * A0, A2 = av[2] * A1, A3 = av[3] * A2;
;             float At[4], Ht[4];
; #pragma unroll
;             for (int q = 0; q < 4; ++q) { At[q] = __shfl(A3, fr + 16 * q); Ht[q] = __shfl(H3, fr + 16 * q); }
;             const float c0 = Hrun[n], c1 = At[0] * c0 + Ht[0], c2 = At[1] * c1 + Ht[1], c3 = At[2] * c2 + Ht[2], c4 = At[3] * c3 + Ht[3];
;             Hrun[n] = c4;
;             if (PASS == 1) Arun[n] *= (At[0] * At[1]) * (At[2] * At[3]);
	v_mfma_f32_16x16x32_bf16 v[94:97], v[50:53], v[202:205], v[138:141]
	v_fma_f32 v126, -v198, v198, 1.0
	v_fma_f32 v127, -v199, v199, 1.0
	v_max_f32_e32 v126, 0, v126
	v_max_f32_e32 v127, 0, v127
	v_sqrt_f32_e32 v126, v126
	v_sqrt_f32_e32 v127, v127
	v_and_or_b32 v138, v213, 64, v137
	v_lshlrev_b32_e32 v151, 2, v138
	v_mfma_f32_16x16x32_bf16 v[138:141], v[110:113], v[2:5], 0
	v_mul_f32_e64 v122, v122, v126
	v_mul_f32_e64 v123, v123, v127
	v_add_f32_e32 v126, v170, v128
	v_mul_f32_e32 v126, 0xbfb8aa3b, v126
	v_exp_f32_e32 v126, v126
	v_rcp_f32_e32 v128, v125
	s_nop 1
	v_pk_mul_f32 v[122:123], v[122:123], v[138:139]
	v_mfma_f32_16x16x32_bf16 v[110:113], v[110:113], v[6:9], 0
	v_add_f32_e32 v126, 1.0, v126
	v_rcp_f32_e32 v126, v126
	v_fmac_f32_e32 v123, v199, v122
	v_mul_f32_e32 v71, 0xbfb8aa3b, v71
	v_exp_f32_e32 v70, v70
	v_mul_f32_e32 v126, v176, v126
	v_exp_f32_e32 v127, v126
	v_add_f32_e32 v126, v170, v129
	v_mul_f32_e32 v126, 0xbfb8aa3b, v126
	v_exp_f32_e32 v126, v126
	v_fma_f32 v122, -v127, v127, 1.0
	v_max_f32_e32 v122, 0, v122
	v_exp_f32_e32 v71, v71
	v_add_f32_e32 v126, 1.0, v126
	v_rcp_f32_e32 v126, v126
	v_add_f32_e32 v70, 1.0, v70
	v_add_f32_e32 v71, 1.0, v71
	v_rcp_f32_e32 v70, v70
	v_mul_f32_e32 v125, v176, v126
	v_sqrt_f32_e32 v126, v122
	v_exp_f32_e32 v139, v125
	v_mov_b32_e32 v125, v123
	v_rcp_f32_e32 v71, v71
	v_pk_mul_f32 v[122:123], v[124:125], v[126:127]
	v_exp_f32_e32 v124, v119
	v_fmac_f32_e32 v123, v122, v140
	v_fma_f32 v122, -v139, v139, 1.0
	v_max_f32_e32 v122, 0, v122
	v_sqrt_f32_e32 v138, v122
	v_mul_f32_e32 v122, v199, v198
	v_mul_f32_e32 v122, v127, v122
	v_mul_f32_e32 v122, v139, v122
	v_mov_b32_e32 v129, v123
	ds_bpermute_b32 v123, v151, v122
	ds_bpermute_b32 v127, v151, v122 offset:64
	ds_bpermute_b32 v199, v151, v122 offset:128
	ds_bpermute_b32 v203, v151, v122 offset:192
	v_exp_f32_e32 v122, v118
	v_fma_f32 v119, -v124, v124, 1.0
	v_max_f32_e32 v119, 0, v119
	v_sqrt_f32_e32 v119, v119
	v_fma_f32 v118, -v122, v122, 1.0
	v_max_f32_e32 v118, 0, v118
	v_sqrt_f32_e32 v118, v118
	v_pk_mul_f32 v[204:205], v[128:129], v[138:139]
	v_add_f32_e32 v66, v187, v66
	v_fmac_f32_e32 v205, v204, v141
	v_pk_mul_f32 v[114:115], v[114:115], v[118:119]
	ds_bpermute_b32 v125, v151, v205
	v_pk_mul_f32 v[110:111], v[114:115], v[110:111]
	v_add_f32_e32 v114, v171, v120
	v_mul_f32_e32 v114, 0xbfb8aa3b, v114
	v_exp_f32_e32 v114, v114
	v_fmac_f32_e32 v111, v124, v110
	ds_bpermute_b32 v129, v151, v205 offset:64
	ds_bpermute_b32 v201, v151, v205 offset:128
	v_add_f32_e32 v114, 1.0, v114
	v_rcp_f32_e32 v115, v114
	v_add_f32_e32 v114, v175, v116
	v_mul_f32_e32 v114, 0xbfb8aa3b, v114
	v_exp_f32_e32 v114, v114
	v_mul_f32_e32 v115, v177, v115
	v_exp_f32_e32 v119, v115
	v_add_f32_e32 v115, v171, v121
	v_mul_f32_e32 v115, 0xbfb8aa3b, v115
	v_exp_f32_e32 v115, v115
	v_fma_f32 v110, -v119, v119, 1.0
	v_add_f32_e32 v114, 1.0, v114
	v_max_f32_e32 v110, 0, v110
	v_add_f32_e32 v115, 1.0, v115
	v_rcp_f32_e32 v115, v115
	v_rcp_f32_e32 v114, v114
	v_sqrt_f32_e32 v118, v110
	v_add_f32_e32 v116, v175, v117
	v_mul_f32_e32 v115, v177, v115
	v_exp_f32_e32 v121, v115
	v_mov_b32_e32 v115, v111
	v_pk_mul_f32 v[110:111], v[114:115], v[118:119]
	v_exp_f32_e32 v114, v106
	v_exp_f32_e32 v115, v107
	v_mul_f32_e32 v116, 0xbfb8aa3b, v116
	v_exp_f32_e32 v116, v116
	v_fma_f32 v106, -v114, v114, 1.0
	v_fma_f32 v107, -v115, v115, 1.0
	v_max_f32_e32 v106, 0, v106
	v_max_f32_e32 v107, 0, v107
	v_sqrt_f32_e32 v106, v106
	v_sqrt_f32_e32 v107, v107
	v_fmac_f32_e32 v111, v110, v112
	v_fma_f32 v110, -v121, v121, 1.0
	v_add_f32_e32 v116, 1.0, v116
	v_max_f32_e32 v110, 0, v110
	v_rcp_f32_e32 v116, v116
	v_sqrt_f32_e32 v120, v110
	v_pk_mul_f32 v[102:103], v[102:103], v[106:107]
	v_add_f32_e32 v106, v178, v108
	v_mul_f32_e32 v106, 0xbfb8aa3b, v106
	v_mov_b32_e32 v117, v111
	v_exp_f32_e32 v106, v106
	v_pk_mul_f32 v[110:111], v[116:117], v[120:121]
	ds_bpermute_b32 v205, v151, v205 offset:192
	v_fmac_f32_e32 v111, v110, v113
	v_mul_f32_e32 v110, v124, v122
	v_mul_f32_e32 v110, v119, v110
	v_mul_f32_e32 v110, v121, v110
	v_add_f32_e32 v106, 1.0, v106
	ds_bpermute_b32 v122, v151, v110
	ds_bpermute_b32 v126, v151, v110 offset:64
	ds_bpermute_b32 v198, v151, v110 offset:128
	ds_bpermute_b32 v202, v151, v110 offset:192
	v_rcp_f32_e32 v106, v106
	ds_bpermute_b32 v124, v151, v111
	ds_bpermute_b32 v128, v151, v111 offset:64
	ds_bpermute_b32 v200, v151, v111 offset:128
	ds_bpermute_b32 v204, v151, v111 offset:192
	v_mul_f32_e32 v106, v182, v106
	s_waitcnt lgkmcnt(6)
	v_pk_mul_f32 v[110:111], v[122:123], v[126:127]
	s_waitcnt lgkmcnt(4)
	v_pk_mul_f32 v[112:113], v[198:199], v[202:203]
	v_exp_f32_e32 v107, v106
	v_add_f32_e32 v106, v178, v109
	v_pk_mul_f32 v[110:111], v[110:111], v[112:113]
	s_waitcnt lgkmcnt(3)
	v_pk_fma_f32 v[112:113], v[172:173], v[122:123], v[124:125]
	v_mul_f32_e32 v106, 0xbfb8aa3b, v106
	s_waitcnt lgkmcnt(2)
	v_pk_fma_f32 v[112:113], v[112:113], v[126:127], v[128:129]
	v_exp_f32_e32 v106, v106
	s_waitcnt lgkmcnt(1)
	v_pk_fma_f32 v[112:113], v[112:113], v[198:199], v[200:201]
	v_pk_mul_f32 v[162:163], v[162:163], v[110:111]
	s_waitcnt lgkmcnt(0)
; __device__ __forceinline__ float fsig2(float x) { return __builtin_amdgcn_rcpf(1.0f + __builtin_amdgcn_exp2f(-LOG2E * x)); }
; template <int PASS> __device__ __forceinline__ void lru_wave_item(LAS unsigned char* lds, LAS unsigned char* vw, int b, int c, int h, const MixP& p, int lane, float (&Hrun)[8], bool cont) {
;     ...
;         for (int n = 0; n < 8; ++n) {
;             const f32x4 aVn = __builtin_amdgcn_mfma_f32_16x16x32_bf16(af[n >> 1], idf[n & 1], (f32x4){0.f, 0.f, 0.f, 0.f}, 0, 0, 0);
;             float av[4], bxv[4];
; #pragma unroll
;             for (int j = 0; j < 4; ++j) {
;                 const float r = fsig2(aR[n][j] + pba[n]), ig = fsig2(aI[n][j] + pbx[n]);
;                 const float a = __builtin_amdgcn_exp2f(r * pk8[n]), mult = __builtin_amdgcn_sqrtf(fmaxf(1.0f - a * a, 0.f));
;                 av[j] = a; bxv[j] = mult * ig * aVn[j];
;             }
;             const float H0 = bxv[0], H1 = av[1] * H0 + bxv[1], H2 = av[2] * H1 + bxv[2], H3 = av[3] * H2 + bxv[3];
;             const float A0 = av[0], A1 = av[1] * A0, A2 = av[2] * A1, A3 = av[3] * A2;
;             float At[4], Ht[4];
; #pragma unroll
;             for (int q = 0; q < 4; ++q) { At[q] = __shfl(A3, fr + 16 * q); Ht[q] = __shfl(H3, fr + 16 * q); }
;             const float c0 = Hrun[n], c1 = At[0] * c0 + Ht[0], c2 = At[1] * c1 + Ht[1], c3 = At[2] * c2 + Ht[2], c4 = At[3] * c3 + Ht[3];
;             Hrun[n] = c4;
;             if (PASS == 1) Arun[n] *= (At[0] * At[1]) * (At[2] * At[3]);
	v_pk_fma_f32 v[172:173], v[112:113], v[202:203], v[204:205]
	v_mfma_f32_16x16x32_bf16 v[110:113], v[82:85], v[2:5], 0
	v_add_f32_e32 v106, 1.0, v106
	v_rcp_f32_e32 v106, v106
	v_rcp_f32_e32 v108, v105
	v_mfma_f32_16x16x32_bf16 v[82:85], v[82:85], v[6:9], 0
	v_mul_f32_e32 v70, v189, v70
	s_nop 2
	v_pk_mul_f32 v[102:103], v[102:103], v[110:111]
	v_mul_f32_e32 v105, v182, v106
	v_fmac_f32_e32 v103, v115, v102
	v_fma_f32 v102, -v107, v107, 1.0
	v_max_f32_e32 v102, 0, v102
	v_sqrt_f32_e32 v106, v102
	v_exp_f32_e32 v111, v105
	v_mov_b32_e32 v105, v103
	v_add_f32_e32 v67, v187, v67
	v_pk_mul_f32 v[102:103], v[104:105], v[106:107]
	v_mul_f32_e32 v71, v189, v71
	v_fmac_f32_e32 v103, v102, v112
	v_fma_f32 v102, -v111, v111, 1.0
	v_max_f32_e32 v102, 0, v102
	v_sqrt_f32_e32 v110, v102
	v_mov_b32_e32 v109, v103
	v_mul_f32_e32 v66, 0xbfb8aa3b, v66
	v_mul_f32_e32 v67, 0xbfb8aa3b, v67
	v_pk_mul_f32 v[102:103], v[108:109], v[110:111]
	v_exp_f32_e32 v66, v66
	v_fmac_f32_e32 v103, v102, v113
	v_mul_f32_e32 v102, v115, v114
	v_mul_f32_e32 v102, v107, v102
	v_mul_f32_e32 v105, v111, v102
	ds_bpermute_b32 v102, v151, v105
	ds_bpermute_b32 v104, v151, v103
	ds_bpermute_b32 v106, v151, v105 offset:64
	ds_bpermute_b32 v108, v151, v103 offset:64
	ds_bpermute_b32 v110, v151, v105 offset:128
	ds_bpermute_b32 v112, v151, v103 offset:128
	ds_bpermute_b32 v114, v151, v105 offset:192
	ds_bpermute_b32 v116, v151, v103 offset:192
	v_exp_f32_e32 v103, v90
	v_exp_f32_e32 v105, v91
	v_exp_f32_e32 v67, v67
	v_add_f32_e32 v66, 1.0, v66
	v_fma_f32 v90, -v103, v103, 1.0
	v_fma_f32 v91, -v105, v105, 1.0
	v_max_f32_e32 v90, 0, v90
	v_max_f32_e32 v91, 0, v91
	v_sqrt_f32_e32 v90, v90
	v_sqrt_f32_e32 v91, v91
	v_add_f32_e32 v67, 1.0, v67
	v_rcp_f32_e32 v66, v66
	v_rcp_f32_e32 v67, v67
	v_pk_mul_f32 v[86:87], v[86:87], v[90:91]
	v_add_f32_e32 v62, v190, v62
	v_pk_mul_f32 v[82:83], v[86:87], v[82:83]
	v_add_f32_e32 v86, v179, v92
	v_mul_f32_e32 v86, 0xbfb8aa3b, v86
	v_exp_f32_e32 v86, v86
	v_fmac_f32_e32 v83, v105, v82
	v_add_f32_e32 v63, v190, v63
	v_mul_f32_e32 v62, 0xbfb8aa3b, v62
	v_add_f32_e32 v86, 1.0, v86
	v_rcp_f32_e32 v87, v86
	v_add_f32_e32 v86, v181, v88
	v_mul_f32_e32 v86, 0xbfb8aa3b, v86
	v_exp_f32_e32 v86, v86
	v_mul_f32_e32 v87, v183, v87
	v_exp_f32_e32 v91, v87
	v_add_f32_e32 v87, v179, v93
	v_mul_f32_e32 v87, 0xbfb8aa3b, v87
	v_exp_f32_e32 v87, v87
	v_fma_f32 v82, -v91, v91, 1.0
	v_add_f32_e32 v86, 1.0, v86
	v_max_f32_e32 v82, 0, v82
	v_add_f32_e32 v87, 1.0, v87
	v_rcp_f32_e32 v87, v87
	v_rcp_f32_e32 v86, v86
	v_sqrt_f32_e32 v90, v82
	v_add_f32_e32 v88, v181, v89
	v_mul_f32_e32 v87, v183, v87
	v_exp_f32_e32 v93, v87
	v_mov_b32_e32 v87, v83
	v_pk_mul_f32 v[82:83], v[86:87], v[90:91]
	v_exp_f32_e32 v86, v78
	v_exp_f32_e32 v87, v79
	v_mul_f32_e32 v88, 0xbfb8aa3b, v88
	v_exp_f32_e32 v88, v88
	v_fma_f32 v78, -v86, v86, 1.0
	v_fma_f32 v79, -v87, v87, 1.0
	v_max_f32_e32 v78, 0, v78
	v_max_f32_e32 v79, 0, v79
	v_sqrt_f32_e32 v78, v78
	v_sqrt_f32_e32 v79, v79
	v_fmac_f32_e32 v83, v82, v84
	v_fma_f32 v82, -v93, v93, 1.0
	v_add_f32_e32 v88, 1.0, v88
	v_max_f32_e32 v82, 0, v82
	v_rcp_f32_e32 v88, v88
	v_sqrt_f32_e32 v92, v82
	v_pk_mul_f32 v[74:75], v[74:75], v[78:79]
	v_add_f32_e32 v78, v184, v80
	v_mul_f32_e32 v78, 0xbfb8aa3b, v78
	v_mov_b32_e32 v89, v83
	v_exp_f32_e32 v78, v78
	v_pk_mul_f32 v[82:83], v[88:89], v[92:93]
	v_rcp_f32_e32 v80, v77
	v_fmac_f32_e32 v83, v82, v85
	v_mul_f32_e32 v82, v105, v103
	v_mul_f32_e32 v82, v91, v82
	v_mul_f32_e32 v82, v93, v82
	v_add_f32_e32 v78, 1.0, v78
	ds_bpermute_b32 v103, v151, v82
	ds_bpermute_b32 v107, v151, v82 offset:64
	ds_bpermute_b32 v111, v151, v82 offset:128
	ds_bpermute_b32 v115, v151, v82 offset:192
	v_rcp_f32_e32 v78, v78
	ds_bpermute_b32 v105, v151, v83
	ds_bpermute_b32 v109, v151, v83 offset:64
	ds_bpermute_b32 v113, v151, v83 offset:128
	ds_bpermute_b32 v117, v151, v83 offset:192
	v_mul_f32_e32 v78, v188, v78
	s_waitcnt lgkmcnt(6)
	v_pk_mul_f32 v[82:83], v[102:103], v[106:107]
	s_waitcnt lgkmcnt(4)
	v_pk_mul_f32 v[84:85], v[110:111], v[114:115]
	v_exp_f32_e32 v79, v78
	v_add_f32_e32 v78, v184, v81
	v_pk_mul_f32 v[82:83], v[82:83], v[84:85]
	s_waitcnt lgkmcnt(3)
	v_pk_fma_f32 v[84:85], v[166:167], v[102:103], v[104:105]
	v_mul_f32_e32 v78, 0xbfb8aa3b, v78
	s_waitcnt lgkmcnt(2)
	v_pk_fma_f32 v[84:85], v[84:85], v[106:107], v[108:109]
	v_exp_f32_e32 v78, v78
	s_waitcnt lgkmcnt(1)
	v_pk_fma_f32 v[84:85], v[84:85], v[110:111], v[112:113]
	v_pk_mul_f32 v[168:169], v[168:169], v[82:83]
	s_waitcnt lgkmcnt(0)
; __device__ __forceinline__ float fsig2(float x) { return __builtin_amdgcn_rcpf(1.0f + __builtin_amdgcn_exp2f(-LOG2E * x)); }
; template <int PASS> __device__ __forceinline__ void lru_wave_item(LAS unsigned char* lds, LAS unsigned char* vw, int b, int c, int h, const MixP& p, int lane, float (&Hrun)[8], bool cont) {
;     ...
;         for (int n = 0; n < 8; ++n) {
;             const f32x4 aVn = __builtin_amdgcn_mfma_f32_16x16x32_bf16(af[n >> 1], idf[n & 1], (f32x4){0.f, 0.f, 0.f, 0.f}, 0, 0, 0);
;             float av[4], bxv[4];
; #pragma unroll
;             for (int j = 0; j < 4; ++j) {
;                 const float r = fsig2(aR[n][j] + pba[n]), ig = fsig2(aI[n][j] + pbx[n]);
;                 const float a = __builtin_amdgcn_exp2f(r * pk8[n]), mult = __builtin_amdgcn_sqrtf(fmaxf(1.0f - a * a, 0.f));
;                 av[j] = a; bxv[j] = mult * ig * aVn[j];
;             }
;             const float H0 = bxv[0], H1 = av[1] * H0 + bxv[1], H2 = av[2] * H1 + bxv[2], H3 = av[3] * H2 + bxv[3];
;             const float A0 = av[0], A1 = av[1] * A0, A2 = av[2] * A1, A3 = av[3] * A2;
;             float At[4], Ht[4];
; #pragma unroll
;             for (int q = 0; q < 4; ++q) { At[q] = __shfl(A3, fr + 16 * q); Ht[q] = __shfl(H3, fr + 16 * q); }
;             const float c0 = Hrun[n], c1 = At[0] * c0 + Ht[0], c2 = At[1] * c1 + Ht[1], c3 = At[2] * c2 + Ht[2], c4 = At[3] * c3 + Ht[3];
;             Hrun[n] = c4;
;             if (PASS == 1) Arun[n] *= (At[0] * At[1]) * (At[2] * At[3]);
	v_pk_fma_f32 v[166:167], v[84:85], v[114:115], v[116:117]
	v_mfma_f32_16x16x32_bf16 v[82:85], v[54:57], v[2:5], 0
	v_add_f32_e32 v78, 1.0, v78
	v_rcp_f32_e32 v78, v78
	v_mul_f32_e32 v63, 0xbfb8aa3b, v63
	v_mfma_f32_16x16x32_bf16 v[54:57], v[54:57], v[6:9], 0
	v_exp_f32_e32 v62, v62
	s_nop 2
	v_pk_mul_f32 v[74:75], v[74:75], v[82:83]
	v_mul_f32_e32 v77, v188, v78
	v_fmac_f32_e32 v75, v87, v74
	v_fma_f32 v74, -v79, v79, 1.0
	v_max_f32_e32 v74, 0, v74
	v_sqrt_f32_e32 v78, v74
	v_exp_f32_e32 v83, v77
	v_mov_b32_e32 v77, v75
	v_exp_f32_e32 v63, v63
	v_pk_mul_f32 v[74:75], v[76:77], v[78:79]
	v_add_f32_e32 v62, 1.0, v62
	v_fmac_f32_e32 v75, v74, v84
	v_fma_f32 v74, -v83, v83, 1.0
	v_max_f32_e32 v74, 0, v74
	v_sqrt_f32_e32 v82, v74
	v_mov_b32_e32 v81, v75
	v_add_f32_e32 v63, 1.0, v63
	v_rcp_f32_e32 v62, v62
	v_pk_mul_f32 v[74:75], v[80:81], v[82:83]
	v_rcp_f32_e32 v63, v63
	v_fmac_f32_e32 v75, v74, v85
	v_mul_f32_e32 v74, v87, v86
	v_mul_f32_e32 v74, v79, v74
	v_mul_f32_e32 v77, v83, v74
	ds_bpermute_b32 v74, v151, v77
	ds_bpermute_b32 v76, v151, v75
	ds_bpermute_b32 v78, v151, v77 offset:64
	ds_bpermute_b32 v80, v151, v75 offset:64
	ds_bpermute_b32 v82, v151, v77 offset:128
	ds_bpermute_b32 v84, v151, v75 offset:128
	ds_bpermute_b32 v86, v151, v77 offset:192
	ds_bpermute_b32 v88, v151, v75 offset:192
	v_exp_f32_e32 v75, v70
	v_exp_f32_e32 v77, v71
	v_add_f32_e32 v58, v192, v58
	v_mul_f32_e32 v62, v194, v62
	v_fma_f32 v70, -v75, v75, 1.0
	v_fma_f32 v71, -v77, v77, 1.0
	v_max_f32_e32 v70, 0, v70
	v_max_f32_e32 v71, 0, v71
	v_sqrt_f32_e32 v70, v70
	v_sqrt_f32_e32 v71, v71
	v_add_f32_e32 v59, v192, v59
	v_mul_f32_e32 v63, v194, v63
	v_mul_f32_e32 v58, 0xbfb8aa3b, v58
	v_pk_mul_f32 v[66:67], v[66:67], v[70:71]
	v_mul_f32_e32 v59, 0xbfb8aa3b, v59
	v_pk_mul_f32 v[54:55], v[66:67], v[54:55]
	v_add_f32_e32 v66, v185, v72
	v_mul_f32_e32 v66, 0xbfb8aa3b, v66
	v_exp_f32_e32 v66, v66
	v_fmac_f32_e32 v55, v77, v54
	v_exp_f32_e32 v58, v58
	v_exp_f32_e32 v59, v59
	v_add_f32_e32 v66, 1.0, v66
	v_rcp_f32_e32 v67, v66
	v_add_f32_e32 v66, v187, v68
	v_mul_f32_e32 v66, 0xbfb8aa3b, v66
	v_exp_f32_e32 v66, v66
	v_mul_f32_e32 v67, v189, v67
	v_exp_f32_e32 v71, v67
	v_add_f32_e32 v67, v185, v73
	v_mul_f32_e32 v67, 0xbfb8aa3b, v67
	v_exp_f32_e32 v67, v67
	v_fma_f32 v54, -v71, v71, 1.0
	v_add_f32_e32 v66, 1.0, v66
	v_max_f32_e32 v54, 0, v54
	v_add_f32_e32 v67, 1.0, v67
	v_rcp_f32_e32 v67, v67
	v_rcp_f32_e32 v66, v66
	v_add_f32_e32 v68, v187, v69
	v_sqrt_f32_e32 v70, v54
	v_mul_f32_e32 v67, v189, v67
	v_mul_f32_e32 v68, 0xbfb8aa3b, v68
	v_exp_f32_e32 v73, v67
	v_exp_f32_e32 v68, v68
	v_mov_b32_e32 v67, v55
	v_pk_mul_f32 v[54:55], v[66:67], v[70:71]
	v_exp_f32_e32 v66, v62
	v_fmac_f32_e32 v55, v54, v56
	v_fma_f32 v54, -v73, v73, 1.0
	v_add_f32_e32 v68, 1.0, v68
	v_max_f32_e32 v54, 0, v54
	v_rcp_f32_e32 v68, v68
	v_sqrt_f32_e32 v72, v54
	v_mov_b32_e32 v69, v55
	v_exp_f32_e32 v67, v63
	v_fma_f32 v62, -v66, v66, 1.0
	v_pk_mul_f32 v[54:55], v[68:69], v[72:73]
	v_add_f32_e32 v58, 1.0, v58
	v_fmac_f32_e32 v55, v54, v57
	v_mul_f32_e32 v54, v77, v75
	v_mul_f32_e32 v54, v71, v54
	v_mul_f32_e32 v54, v73, v54
	ds_bpermute_b32 v75, v151, v54
	ds_bpermute_b32 v79, v151, v54 offset:64
	ds_bpermute_b32 v83, v151, v54 offset:128
	ds_bpermute_b32 v87, v151, v54 offset:192
	ds_bpermute_b32 v77, v151, v55
	ds_bpermute_b32 v81, v151, v55 offset:64
	ds_bpermute_b32 v85, v151, v55 offset:128
	ds_bpermute_b32 v89, v151, v55 offset:192
	s_waitcnt lgkmcnt(6)
	v_pk_mul_f32 v[54:55], v[74:75], v[78:79]
	s_waitcnt lgkmcnt(4)
	v_pk_mul_f32 v[56:57], v[82:83], v[86:87]
	v_fma_f32 v63, -v67, v67, 1.0
	v_pk_mul_f32 v[54:55], v[54:55], v[56:57]
	s_waitcnt lgkmcnt(3)
	v_pk_fma_f32 v[56:57], v[160:161], v[74:75], v[76:77]
	v_max_f32_e32 v62, 0, v62
	s_waitcnt lgkmcnt(2)
	v_pk_fma_f32 v[56:57], v[56:57], v[78:79], v[80:81]
	v_add_f32_e32 v59, 1.0, v59
	v_max_f32_e32 v63, 0, v63
	s_waitcnt lgkmcnt(1)
	v_pk_fma_f32 v[56:57], v[56:57], v[82:83], v[84:85]
	v_rcp_f32_e32 v58, v58
	v_sqrt_f32_e32 v62, v62
	v_rcp_f32_e32 v59, v59
	v_sqrt_f32_e32 v63, v63
	s_waitcnt lgkmcnt(0)
; __device__ __forceinline__ float fsig2(float x) { return __builtin_amdgcn_rcpf(1.0f + __builtin_amdgcn_exp2f(-LOG2E * x)); }
; template <int PASS> __device__ __forceinline__ void lru_wave_item(LAS unsigned char* lds, LAS unsigned char* vw, int b, int c, int h, const MixP& p, int lane, float (&Hrun)[8], bool cont) {
;     ...
;         for (int n = 0; n < 8; ++n) {
;             const f32x4 aVn = __builtin_amdgcn_mfma_f32_16x16x32_bf16(af[n >> 1], idf[n & 1], (f32x4){0.f, 0.f, 0.f, 0.f}, 0, 0, 0);
;             float av[4], bxv[4];
; #pragma unroll
;             for (int j = 0; j < 4; ++j) {
;                 const float r = fsig2(aR[n][j] + pba[n]), ig = fsig2(aI[n][j] + pbx[n]);
;                 const float a = __builtin_amdgcn_exp2f(r * pk8[n]), mult = __builtin_amdgcn_sqrtf(fmaxf(1.0f - a * a, 0.f));
;                 av[j] = a; bxv[j] = mult * ig * aVn[j];
;             }
;             const float H0 = bxv[0], H1 = av[1] * H0 + bxv[1], H2 = av[2] * H1 + bxv[2], H3 = av[3] * H2 + bxv[3];
;             const float A0 = av[0], A1 = av[1] * A0, A2 = av[2] * A1, A3 = av[3] * A2;
;             float At[4], Ht[4];
; #pragma unroll
;             for (int q = 0; q < 4; ++q) { At[q] = __shfl(A3, fr + 16 * q); Ht[q] = __shfl(H3, fr + 16 * q); }
;             const float c0 = Hrun[n], c1 = At[0] * c0 + Ht[0], c2 = At[1] * c1 + Ht[1], c3 = At[2] * c2 + Ht[2], c4 = At[3] * c3 + Ht[3];
;             Hrun[n] = c4;
;             if (PASS == 1) Arun[n] *= (At[0] * At[1]) * (At[2] * At[3]);
;     ...
;     if (PASS == 1 && fq == 0) {
; #pragma unroll
;         for (int n = 0; n < 8; ++n) *(f32x2*)(p.summ + (((size_t)b * NCH + c) * LW + h * 128 + 16 * n + fr) * 2) = (f32x2){Arun[n], Hrun[n]};
;     }
	v_pk_fma_f32 v[160:161], v[56:57], v[86:87], v[88:89]
	v_pk_mul_f32 v[164:165], v[164:165], v[54:55]
	v_mfma_f32_16x16x32_bf16 v[54:57], v[50:53], v[2:5], 0
	v_mul_f32_e64 v58, v58, v62
	v_mul_f32_e64 v59, v59, v63
	v_mfma_f32_16x16x32_bf16 v[50:53], v[50:53], v[6:9], 0
	s_nop 4
	v_mul_f32_e64 v54, v58, v54
	v_mul_f32_e64 v55, v59, v55
	v_add_f32_e32 v58, v190, v64
	v_mul_f32_e32 v58, 0xbfb8aa3b, v58
	v_exp_f32_e32 v58, v58
	v_fmac_f32_e32 v55, v67, v54
	v_add_f32_e32 v58, 1.0, v58
	v_rcp_f32_e32 v59, v58
	v_add_f32_e32 v58, v192, v60
	v_mul_f32_e32 v58, 0xbfb8aa3b, v58
	v_exp_f32_e32 v58, v58
	v_mul_f32_e32 v59, v194, v59
	v_exp_f32_e32 v63, v59
	v_add_f32_e32 v59, v190, v65
	v_mul_f32_e32 v59, 0xbfb8aa3b, v59
	v_exp_f32_e32 v59, v59
	v_fma_f32 v54, -v63, v63, 1.0
	v_add_f32_e32 v58, 1.0, v58
	v_max_f32_e32 v54, 0, v54
	v_add_f32_e32 v59, 1.0, v59
	v_rcp_f32_e32 v59, v59
	v_rcp_f32_e32 v58, v58
	v_add_f32_e32 v60, v192, v61
	v_sqrt_f32_e32 v62, v54
	v_mul_f32_e32 v59, v194, v59
	v_mul_f32_e32 v60, 0xbfb8aa3b, v60
	v_exp_f32_e32 v65, v59
	v_exp_f32_e32 v60, v60
	v_mov_b32_e32 v59, v55
	v_pk_mul_f32 v[54:55], v[58:59], v[62:63]
	v_add_f32_e32 v59, v193, v95
	v_fmac_f32_e32 v55, v54, v56
	v_fma_f32 v54, -v65, v65, 1.0
	v_add_f32_e32 v60, 1.0, v60
	v_max_f32_e32 v54, 0, v54
	v_rcp_f32_e32 v60, v60
	v_sqrt_f32_e32 v64, v54
	v_mov_b32_e32 v61, v55
	v_mul_f32_e32 v59, 0xbfb8aa3b, v59
	v_exp_f32_e32 v59, v59
	v_pk_mul_f32 v[54:55], v[60:61], v[64:65]
	v_add_f32_e32 v61, v193, v96
	v_fmac_f32_e32 v55, v54, v57
	ds_bpermute_b32 v56, v151, v55
	ds_bpermute_b32 v60, v151, v55 offset:64
	ds_bpermute_b32 v64, v151, v55 offset:128
	ds_bpermute_b32 v68, v151, v55 offset:192
	v_add_f32_e32 v55, v191, v98
	v_mul_f32_e32 v55, 0xbfb8aa3b, v55
	v_exp_f32_e32 v55, v55
	v_mul_f32_e32 v54, v67, v66
	v_mul_f32_e32 v54, v63, v54
	v_mul_f32_e32 v57, v65, v54
	v_add_f32_e32 v55, 1.0, v55
	v_rcp_f32_e32 v55, v55
	ds_bpermute_b32 v54, v151, v57
	ds_bpermute_b32 v58, v151, v57 offset:64
	ds_bpermute_b32 v62, v151, v57 offset:128
	ds_bpermute_b32 v66, v151, v57 offset:192
	v_add_f32_e32 v57, v193, v94
	v_mul_f32_e32 v57, 0xbfb8aa3b, v57
	v_exp_f32_e32 v57, v57
	v_mul_f32_e32 v55, v195, v55
	v_exp_f32_e32 v55, v55
	v_add_f32_e32 v59, 1.0, v59
	v_add_f32_e32 v57, 1.0, v57
	v_rcp_f32_e32 v70, v57
	v_fma_f32 v57, -v55, v55, 1.0
	v_max_f32_e32 v57, 0, v57
	v_sqrt_f32_e32 v72, v57
	v_add_f32_e32 v57, v191, v99
	v_mul_f32_e32 v57, 0xbfb8aa3b, v57
	v_exp_f32_e32 v57, v57
	v_rcp_f32_e32 v71, v59
	v_mul_f32_e32 v61, 0xbfb8aa3b, v61
	v_exp_f32_e32 v61, v61
	v_add_f32_e32 v57, 1.0, v57
	v_rcp_f32_e32 v57, v57
	v_add_f32_e32 v61, 1.0, v61
	v_mul_f32_e32 v57, v195, v57
	v_exp_f32_e32 v57, v57
	s_nop 0
	v_fma_f32 v59, -v57, v57, 1.0
	v_max_f32_e32 v59, 0, v59
	v_sqrt_f32_e32 v73, v59
	v_add_f32_e32 v59, v191, v100
	v_mul_f32_e32 v59, 0xbfb8aa3b, v59
	v_exp_f32_e32 v59, v59
	v_pk_mul_f32 v[70:71], v[70:71], v[72:73]
	v_add_f32_e32 v59, 1.0, v59
	v_rcp_f32_e32 v59, v59
	v_pk_mul_f32 v[50:51], v[70:71], v[50:51]
	v_rcp_f32_e32 v70, v61
	v_fmac_f32_e32 v51, v57, v50
	v_mul_f32_e32 v59, v195, v59
	v_exp_f32_e32 v73, v59
	v_add_f32_e32 v59, v191, v101
	v_mul_f32_e32 v59, 0xbfb8aa3b, v59
	v_exp_f32_e32 v59, v59
	v_fma_f32 v50, -v73, v73, 1.0
	v_max_f32_e32 v50, 0, v50
	v_add_f32_e32 v61, v193, v97
	v_add_f32_e32 v59, 1.0, v59
	v_rcp_f32_e32 v59, v59
	v_sqrt_f32_e32 v72, v50
	v_mul_f32_e32 v61, 0xbfb8aa3b, v61
	v_exp_f32_e32 v61, v61
	v_mul_f32_e32 v59, v195, v59
	v_exp_f32_e32 v77, v59
	v_mov_b32_e32 v71, v51
	v_pk_mul_f32 v[50:51], v[70:71], v[72:73]
	v_add_f32_e32 v61, 1.0, v61
	v_fmac_f32_e32 v51, v50, v52
	v_fma_f32 v50, -v77, v77, 1.0
	v_max_f32_e32 v50, 0, v50
	v_rcp_f32_e32 v74, v61
	v_sqrt_f32_e32 v76, v50
	v_mov_b32_e32 v75, v51
	v_pk_mul_f32 v[50:51], v[74:75], v[76:77]
	s_nop 0
	v_fmac_f32_e32 v51, v50, v53
	v_mul_f32_e32 v50, v57, v55
	v_mul_f32_e32 v50, v73, v50
	v_mul_f32_e32 v50, v77, v50
	ds_bpermute_b32 v55, v151, v50
	ds_bpermute_b32 v59, v151, v50 offset:64
	ds_bpermute_b32 v63, v151, v50 offset:128
	ds_bpermute_b32 v67, v151, v50 offset:192
	ds_bpermute_b32 v57, v151, v51
	ds_bpermute_b32 v61, v151, v51 offset:64
	ds_bpermute_b32 v65, v151, v51 offset:128
	ds_bpermute_b32 v69, v151, v51 offset:192
	s_waitcnt lgkmcnt(6)
	v_pk_mul_f32 v[50:51], v[54:55], v[58:59]
	s_waitcnt lgkmcnt(4)
	v_pk_mul_f32 v[52:53], v[62:63], v[66:67]
	s_nop 0
	v_pk_mul_f32 v[50:51], v[50:51], v[52:53]
	s_waitcnt lgkmcnt(3)
	v_pk_fma_f32 v[52:53], v[156:157], v[54:55], v[56:57]
	v_pk_mul_f32 v[158:159], v[158:159], v[50:51]
	s_waitcnt lgkmcnt(2)
	v_pk_fma_f32 v[52:53], v[52:53], v[58:59], v[60:61]
	s_waitcnt lgkmcnt(1)
	v_pk_fma_f32 v[52:53], v[52:53], v[62:63], v[64:65]
	s_waitcnt lgkmcnt(0)
	v_pk_fma_f32 v[156:157], v[52:53], v[66:67], v[68:69]
	s_cbranch_vccz .LBB0_668
	s_and_saveexec_b64 s[28:29], s[4:5]
	s_cbranch_execz .LBB0_666
	s_ashr_i32 s59, s58, 31
	s_lshl_b64 s[16:17], s[58:59], 6
	s_ashr_i32 s2, s11, 31
	s_add_u32 s3, s16, s11
	s_addc_u32 s2, s17, s2
	s_mulk_i32 s2, 0x500
	v_mad_u64_u32 v[10:11], s[16:17], s3, v217, v[152:153]
	v_add_u32_e32 v11, s2, v11
	v_mov_b32_e32 v12, v163
	v_mov_b32_e32 v13, v173
	v_lshl_add_u64 v[10:11], v[10:11], 3, s[94:95]
	global_store_dwordx2 v[10:11], v[12:13], off sc1
	v_mov_b32_e32 v12, v168
	v_mov_b32_e32 v13, v166
	global_store_dwordx2 v[10:11], v[12:13], off offset:256 sc1
	v_mov_b32_e32 v12, v164
	v_mov_b32_e32 v13, v160
	v_mov_b32_e32 v163, v172
	v_mov_b32_e32 v166, v169
	global_store_dwordx2 v[10:11], v[12:13], off offset:512 sc1
	v_mov_b32_e32 v160, v165
	v_mov_b32_e32 v12, v158
	v_mov_b32_e32 v13, v156
	v_mov_b32_e32 v156, v159
	global_store_dwordx2 v[10:11], v[162:163], off offset:128 sc1
	global_store_dwordx2 v[10:11], v[166:167], off offset:384 sc1
	global_store_dwordx2 v[10:11], v[160:161], off offset:640 sc1
	global_store_dwordx2 v[10:11], v[12:13], off offset:768 sc1
	global_store_dwordx2 v[10:11], v[156:157], off offset:896 sc1
	s_branch .LBB0_666

; #define LAS __attribute__((address_space(3)))
; __device__ __forceinline__ unsigned cvt_pk_bf16(float lo, float hi) { unsigned r; asm volatile("v_cvt_pk_bf16_f32 %0, %1, %2" : "=v"(r) : "v"(lo), "v"(hi)); return r; }
; __device__ __forceinline__ float bflo(unsigned w) { return __uint_as_float(w << 16); }
; __device__ __forceinline__ float bfhi(unsigned w) { return __uint_as_float(w & 0xffff0000u); }
; template <int PASS> __device__ __forceinline__ void lru_wave_item(LAS unsigned char* lds, LAS unsigned char* vw, int b, int c, int h, const MixP& p, int lane, float (&Hrun)[8], bool cont) {
;     ...
;     for (int st = 0; st < CT / 16; ++st) {
;         const int s0 = c * CT + 16 * st;
;         u32x4 ur[7];
;         {
;             const int sb = s0 + 4 * fq - 3;
; #pragma unroll
;             for (int r = 0; r < 7; ++r) ur[r] = *(const u32x4*)(ub + (size_t)max(sb + r, 0) * P1W);
;         }
;         if (s0 == 0 && fq == 0) {
; #pragma unroll
;             for (int r = 0; r < 3; ++r) ur[r] = (u32x4){0u, 0u, 0u, 0u};
;         }
; #pragma unroll
;         for (int jj = 0; jj < 4; ++jj) {
;             f32x2 o[4] = {bv[0], bv[1], bv[2], bv[3]};
; #pragma unroll
;             for (int k = 0; k < 4; ++k) { const u32x4 uk = ur[jj + k];
;                 o[0] = wv[k][0] * (f32x2){bflo(uk.x), bfhi(uk.x)} + o[0]; o[1] = wv[k][1] * (f32x2){bflo(uk.y), bfhi(uk.y)} + o[1];
;                 o[2] = wv[k][2] * (f32x2){bflo(uk.z), bfhi(uk.z)} + o[2]; o[3] = wv[k][3] * (f32x2){bflo(uk.w), bfhi(uk.w)} + o[3]; }
;             { u32x4 w; w.x = cvt_pk_bf16(o[0].x, o[0].y); w.y = cvt_pk_bf16(o[1].x, o[1].y); w.z = cvt_pk_bf16(o[2].x, o[2].y); w.w = cvt_pk_bf16(o[3].x, o[3].y);
;               *(LAS u32x4*)(vw + (4 * fq + jj) * WROW + cg * 16) = w; }
;         }
;     ...
;                 const u32x4 g = *(const u32x4*)(p.P2 + row * P2W + h * 128 + cg * 8);
.LBB0_818:
	s_or_b32 s22, s19, s11
	v_add_u32_e32 v0, s22, v224
	v_max_i32_e32 v2, 0, v0
	v_mad_u64_u32 v[2:3], s[20:21], v2, s82, v[182:183]
	global_load_dwordx4 v[74:77], v[2:3], off offset:1024
	v_max_i32_e32 v2, -1, v0
	v_add_u32_e32 v2, 1, v2
	v_mad_u64_u32 v[2:3], s[20:21], v2, s82, v[182:183]
	global_load_dwordx4 v[78:81], v[2:3], off offset:1024
	v_or_b32_e32 v2, 2, v0
	v_max_i32_e32 v2, 0, v2
	v_mad_u64_u32 v[2:3], s[20:21], v2, s82, v[182:183]
	global_load_dwordx4 v[82:85], v[2:3], off offset:1024
	v_or_b32_e32 v2, s22, v223
	v_max_i32_e32 v2, 0, v2
	v_mad_u64_u32 v[2:3], s[20:21], v2, s82, v[182:183]
	global_load_dwordx4 v[70:73], v[2:3], off offset:1024
	v_max_i32_e32 v2, -4, v0
	v_add_u32_e32 v2, 4, v2
	v_mad_u64_u32 v[2:3], s[20:21], v2, s82, v[182:183]
	global_load_dwordx4 v[66:69], v[2:3], off offset:1024
	v_max_i32_e32 v2, -5, v0
	v_add_u32_e32 v2, 5, v2
	v_mad_u64_u32 v[2:3], s[20:21], v2, s82, v[182:183]
	global_load_dwordx4 v[6:9], v[2:3], off offset:1024
	v_max_i32_e32 v0, -6, v0
	v_add_u32_e32 v0, 6, v0
	v_mad_u64_u32 v[2:3], s[20:21], v0, s82, v[182:183]
	global_load_dwordx4 v[2:5], v[2:3], off offset:1024
	s_cmp_eq_u32 s22, 0
	s_cselect_b64 s[20:21], -1, 0
	s_and_b64 s[20:21], s[20:21], s[4:5]
	s_or_b32 s19, s19, s18
	s_and_b64 vcc, exec, s[12:13]
	s_mov_b64 s[12:13], 0
	v_or_b32_e32 v96, s19, v203
	v_mad_i64_i32 v[240:241], s[98:99], v96, s83, v[152:153]
	global_load_dwordx4 v[240:243], v[240:241], off
	v_or_b32_e32 v96, s19, v225
	v_mad_i64_i32 v[244:245], s[98:99], v96, s83, v[152:153]
	global_load_dwordx4 v[244:247], v[244:245], off
	v_or_b32_e32 v96, s19, v226
	v_mad_i64_i32 v[248:249], s[98:99], v96, s83, v[152:153]
	global_load_dwordx4 v[248:251], v[248:249], off
	v_or_b32_e32 v96, s19, v227
	v_mad_i64_i32 v[206:207], s[98:99], v96, s83, v[152:153]
	global_load_dwordx2 v[210:211], v[206:207], off offset:8
	global_load_dwordx2 v[206:207], v[206:207], off
	s_add_i32 s100, s22, 16
	v_add_u32_e32 v96, s100, v224
	v_max_i32_e32 v97, 0, v96
	v_mad_u64_u32 v[98:99], s[98:99], v97, s82, v[182:183]
	global_load_dword v237, v[98:99], off offset:1024
	v_add_u32_e32 v97, 1, v96
	v_max_i32_e32 v97, 0, v97
	v_mad_u64_u32 v[98:99], s[98:99], v97, s82, v[182:183]
	global_load_dword v237, v[98:99], off offset:1024
	v_add_u32_e32 v97, 2, v96
	v_max_i32_e32 v97, 0, v97
	v_mad_u64_u32 v[98:99], s[98:99], v97, s82, v[182:183]
	global_load_dword v237, v[98:99], off offset:1024
	v_add_u32_e32 v97, 3, v96
	v_max_i32_e32 v97, 0, v97
	v_mad_u64_u32 v[98:99], s[98:99], v97, s82, v[182:183]
	global_load_dword v237, v[98:99], off offset:1024
	v_add_u32_e32 v97, 4, v96
	v_max_i32_e32 v97, 0, v97
	v_mad_u64_u32 v[98:99], s[98:99], v97, s82, v[182:183]
	global_load_dword v237, v[98:99], off offset:1024
	v_add_u32_e32 v97, 5, v96
	v_max_i32_e32 v97, 0, v97
	v_mad_u64_u32 v[98:99], s[98:99], v97, s82, v[182:183]
	global_load_dword v237, v[98:99], off offset:1024
	v_add_u32_e32 v97, 6, v96
	v_max_i32_e32 v97, 0, v97
	v_mad_u64_u32 v[98:99], s[98:99], v97, s82, v[182:183]
	global_load_dword v237, v[98:99], off offset:1024
	s_waitcnt vmcnt(18)
	v_cndmask_b32_e64 v0, v77, 0, s[20:21]
	v_cndmask_b32_e64 v77, v75, 0, s[20:21]
	v_cndmask_b32_e64 v75, v74, 0, s[20:21]
	v_cndmask_b32_e64 v86, v76, 0, s[20:21]
	v_lshlrev_b32_e32 v74, 16, v75
	s_waitcnt vmcnt(17)
	v_cndmask_b32_e64 v89, v79, 0, s[20:21]
	v_cndmask_b32_e64 v91, v78, 0, s[20:21]
	v_and_b32_e32 v75, 0xffff0000, v75
	v_lshlrev_b32_e32 v76, 16, v77
	v_and_b32_e32 v77, 0xffff0000, v77
	v_cndmask_b32_e64 v88, v81, 0, s[20:21]
	v_cndmask_b32_e64 v87, v80, 0, s[20:21]
	s_waitcnt vmcnt(16)
	v_cndmask_b32_e64 v102, v83, 0, s[20:21]
	v_cndmask_b32_e64 v98, v82, 0, s[20:21]
	s_waitcnt lgkmcnt(13)
	v_pk_fma_f32 v[74:75], v[26:27], v[74:75], v[58:59]
	v_pk_fma_f32 v[76:77], v[28:29], v[76:77], v[60:61]
	v_lshlrev_b32_e32 v78, 16, v86
	v_and_b32_e32 v79, 0xffff0000, v86
	v_lshlrev_b32_e32 v80, 16, v0
	v_and_b32_e32 v81, 0xffff0000, v0
	v_lshlrev_b32_e32 v90, 16, v91
	v_and_b32_e32 v91, 0xffff0000, v91
	v_lshlrev_b32_e32 v92, 16, v89
	v_and_b32_e32 v93, 0xffff0000, v89
	v_cndmask_b32_e64 v100, v85, 0, s[20:21]
	v_cndmask_b32_e64 v101, v84, 0, s[20:21]
	s_waitcnt lgkmcnt(12)
	v_pk_fma_f32 v[78:79], v[30:31], v[78:79], v[62:63]
	v_pk_fma_f32 v[80:81], v[32:33], v[80:81], v[64:65]
	v_pk_fma_f32 v[82:83], v[34:35], v[90:91], v[74:75]
	v_pk_fma_f32 v[84:85], v[36:37], v[92:93], v[76:77]
	v_lshlrev_b32_e32 v94, 16, v87
	v_and_b32_e32 v95, 0xffff0000, v87
	v_lshlrev_b32_e32 v96, 16, v88
	v_and_b32_e32 v97, 0xffff0000, v88
	v_lshlrev_b32_e32 v74, 16, v98
	v_and_b32_e32 v75, 0xffff0000, v98
	v_lshlrev_b32_e32 v76, 16, v102
	v_and_b32_e32 v77, 0xffff0000, v102
	v_pk_fma_f32 v[86:87], v[38:39], v[94:95], v[78:79]
	v_pk_fma_f32 v[88:89], v[40:41], v[96:97], v[80:81]
	v_pk_fma_f32 v[98:99], v[42:43], v[74:75], v[82:83]
	v_pk_fma_f32 v[84:85], v[44:45], v[76:77], v[84:85]
	v_lshlrev_b32_e32 v78, 16, v101
	v_and_b32_e32 v79, 0xffff0000, v101
	v_lshlrev_b32_e32 v80, 16, v100
	v_and_b32_e32 v81, 0xffff0000, v100
	s_waitcnt vmcnt(15)
	v_lshlrev_b32_e32 v82, 16, v70
	v_and_b32_e32 v83, 0xffff0000, v70
	v_lshlrev_b32_e32 v70, 16, v71
	v_and_b32_e32 v71, 0xffff0000, v71
	v_pk_fma_f32 v[86:87], v[46:47], v[78:79], v[86:87]
	v_pk_fma_f32 v[88:89], v[48:49], v[80:81], v[88:89]
	v_pk_fma_f32 v[100:101], v[52:53], v[70:71], v[84:85]
	v_lshlrev_b32_e32 v84, 16, v72
	v_and_b32_e32 v85, 0xffff0000, v72
	v_lshlrev_b32_e32 v72, 16, v73
	v_and_b32_e32 v73, 0xffff0000, v73
	v_pk_fma_f32 v[98:99], v[50:51], v[82:83], v[98:99]
	v_pk_fma_f32 v[102:103], v[54:55], v[84:85], v[86:87]
	v_pk_fma_f32 v[104:105], v[56:57], v[72:73], v[88:89]
	v_cvt_pk_bf16_f32 v86, v98, v99
	v_cvt_pk_bf16_f32 v87, v100, v101
	v_cvt_pk_bf16_f32 v88, v102, v103
	s_waitcnt vmcnt(14)
; #define LAS __attribute__((address_space(3)))
; __device__ __forceinline__ unsigned cvt_pk_bf16(float lo, float hi) { unsigned r; asm volatile("v_cvt_pk_bf16_f32 %0, %1, %2" : "=v"(r) : "v"(lo), "v"(hi)); return r; }
; __device__ __forceinline__ float bflo(unsigned w) { return __uint_as_float(w << 16); }
; __device__ __forceinline__ float bfhi(unsigned w) { return __uint_as_float(w & 0xffff0000u); }
; template <int PASS> __device__ __forceinline__ void lru_wave_item(LAS unsigned char* lds, LAS unsigned char* vw, int b, int c, int h, const MixP& p, int lane, float (&Hrun)[8], bool cont) {
;     ...
;             for (int k = 0; k < 4; ++k) { const u32x4 uk = ur[jj + k];
;                 o[0] = wv[k][0] * (f32x2){bflo(uk.x), bfhi(uk.x)} + o[0]; o[1] = wv[k][1] * (f32x2){bflo(uk.y), bfhi(uk.y)} + o[1];
;                 o[2] = wv[k][2] * (f32x2){bflo(uk.z), bfhi(uk.z)} + o[2]; o[3] = wv[k][3] * (f32x2){bflo(uk.w), bfhi(uk.w)} + o[3]; }
;             { u32x4 w; w.x = cvt_pk_bf16(o[0].x, o[0].y); w.y = cvt_pk_bf16(o[1].x, o[1].y); w.z = cvt_pk_bf16(o[2].x, o[2].y); w.w = cvt_pk_bf16(o[3].x, o[3].y);
;               *(LAS u32x4*)(vw + (4 * fq + jj) * WROW + cg * 16) = w; }
;         }
;         f32x4 aR[8], aI[8];
;         bf16x8 af[4];
;         {
; #pragma unroll
;             for (int kk = 0; kk < 4; ++kk) af[kk] = *(const LAS bf16x8*)(vw + fr * WROW + kk * 64 + fq * 16);
; #pragma unroll
;             for (int n = 0; n < 8; ++n) {
;                 aR[n] = (f32x4){0.f, 0.f, 0.f, 0.f}; aI[n] = (f32x4){0.f, 0.f, 0.f, 0.f};
; #pragma unroll
;                 for (int kk = 0; kk < 4; ++kk) {
;                     const bf16x8 ba = *(const LAS bf16x8*)(lds + WA_OFF + (16 * n + fr) * WROW + kk * 64 + fq * 16);
;                     const bf16x8 bx = *(const LAS bf16x8*)(lds + WX_OFF + (16 * n + fr) * WROW + kk * 64 + fq * 16);
;                     aR[n] = __builtin_amdgcn_mfma_f32_16x16x32_bf16(af[kk], ba, aR[n], 0, 0, 0);
;                     aI[n] = __builtin_amdgcn_mfma_f32_16x16x32_bf16(af[kk], bx, aI[n], 0, 0, 0);
;                 }
;             }
	v_lshlrev_b32_e32 v98, 16, v68
	v_cvt_pk_bf16_f32 v89, v104, v105
	ds_write_b128 v229, v[86:89]
	v_pk_fma_f32 v[86:87], v[26:27], v[90:91], v[58:59]
	v_pk_fma_f32 v[88:89], v[28:29], v[92:93], v[60:61]
	v_pk_fma_f32 v[90:91], v[30:31], v[94:95], v[62:63]
	v_pk_fma_f32 v[92:93], v[32:33], v[96:97], v[64:65]
	v_pk_fma_f32 v[86:87], v[34:35], v[74:75], v[86:87]
	v_pk_fma_f32 v[88:89], v[36:37], v[76:77], v[88:89]
	v_pk_fma_f32 v[90:91], v[38:39], v[78:79], v[90:91]
	v_pk_fma_f32 v[92:93], v[40:41], v[80:81], v[92:93]
	v_pk_fma_f32 v[86:87], v[42:43], v[82:83], v[86:87]
	v_pk_fma_f32 v[88:89], v[44:45], v[70:71], v[88:89]
	v_pk_fma_f32 v[90:91], v[46:47], v[84:85], v[90:91]
	v_pk_fma_f32 v[92:93], v[48:49], v[72:73], v[92:93]
	v_lshlrev_b32_e32 v94, 16, v66
	v_and_b32_e32 v95, 0xffff0000, v66
	v_lshlrev_b32_e32 v96, 16, v67
	v_and_b32_e32 v97, 0xffff0000, v67
	v_and_b32_e32 v99, 0xffff0000, v68
	v_lshlrev_b32_e32 v100, 16, v69
	v_and_b32_e32 v101, 0xffff0000, v69
	v_pk_fma_f32 v[86:87], v[50:51], v[94:95], v[86:87]
	v_pk_fma_f32 v[88:89], v[52:53], v[96:97], v[88:89]
	v_pk_fma_f32 v[90:91], v[54:55], v[98:99], v[90:91]
	v_pk_fma_f32 v[92:93], v[56:57], v[100:101], v[92:93]
	v_cvt_pk_bf16_f32 v66, v86, v87
	v_cvt_pk_bf16_f32 v67, v88, v89
	v_cvt_pk_bf16_f32 v68, v90, v91
	s_waitcnt vmcnt(13)
	v_lshlrev_b32_e32 v86, 16, v8
	v_cvt_pk_bf16_f32 v69, v92, v93
	ds_write_b128 v229, v[66:69] offset:272
	v_pk_fma_f32 v[66:67], v[26:27], v[74:75], v[58:59]
	v_pk_fma_f32 v[68:69], v[28:29], v[76:77], v[60:61]
	v_pk_fma_f32 v[74:75], v[30:31], v[78:79], v[62:63]
	v_pk_fma_f32 v[76:77], v[32:33], v[80:81], v[64:65]
	v_pk_fma_f32 v[66:67], v[34:35], v[82:83], v[66:67]
	v_pk_fma_f32 v[68:69], v[36:37], v[70:71], v[68:69]
	v_pk_fma_f32 v[74:75], v[38:39], v[84:85], v[74:75]
	v_pk_fma_f32 v[76:77], v[40:41], v[72:73], v[76:77]
	v_pk_fma_f32 v[66:67], v[42:43], v[94:95], v[66:67]
	v_pk_fma_f32 v[68:69], v[44:45], v[96:97], v[68:69]
	v_pk_fma_f32 v[74:75], v[46:47], v[98:99], v[74:75]
	v_pk_fma_f32 v[76:77], v[48:49], v[100:101], v[76:77]
	v_lshlrev_b32_e32 v78, 16, v6
	v_and_b32_e32 v79, 0xffff0000, v6
	v_lshlrev_b32_e32 v80, 16, v7
	v_and_b32_e32 v81, 0xffff0000, v7
	v_and_b32_e32 v87, 0xffff0000, v8
	v_lshlrev_b32_e32 v88, 16, v9
	v_and_b32_e32 v89, 0xffff0000, v9
	v_pk_fma_f32 v[66:67], v[50:51], v[78:79], v[66:67]
	v_pk_fma_f32 v[68:69], v[52:53], v[80:81], v[68:69]
	v_pk_fma_f32 v[74:75], v[54:55], v[86:87], v[74:75]
	v_pk_fma_f32 v[76:77], v[56:57], v[88:89], v[76:77]
	v_cvt_pk_bf16_f32 v6, v66, v67
	v_cvt_pk_bf16_f32 v7, v68, v69
	v_cvt_pk_bf16_f32 v8, v74, v75
	v_pk_fma_f32 v[66:67], v[30:31], v[84:85], v[62:63]
	v_cvt_pk_bf16_f32 v9, v76, v77
	ds_write_b128 v229, v[6:9] offset:544
	v_pk_fma_f32 v[6:7], v[26:27], v[82:83], v[58:59]
	v_pk_fma_f32 v[8:9], v[28:29], v[70:71], v[60:61]
	v_pk_fma_f32 v[68:69], v[32:33], v[72:73], v[64:65]
	v_pk_fma_f32 v[6:7], v[34:35], v[94:95], v[6:7]
	v_pk_fma_f32 v[8:9], v[36:37], v[96:97], v[8:9]
	v_pk_fma_f32 v[66:67], v[38:39], v[98:99], v[66:67]
	v_pk_fma_f32 v[68:69], v[40:41], v[100:101], v[68:69]
	v_pk_fma_f32 v[6:7], v[42:43], v[78:79], v[6:7]
	v_pk_fma_f32 v[8:9], v[44:45], v[80:81], v[8:9]
	v_pk_fma_f32 v[70:71], v[46:47], v[86:87], v[66:67]
	v_pk_fma_f32 v[66:67], v[48:49], v[88:89], v[68:69]
	s_waitcnt vmcnt(12)
	v_lshlrev_b32_e32 v68, 16, v2
	v_and_b32_e32 v69, 0xffff0000, v2
	v_lshlrev_b32_e32 v2, 16, v3
	v_and_b32_e32 v3, 0xffff0000, v3
	v_pk_fma_f32 v[6:7], v[50:51], v[68:69], v[6:7]
	v_pk_fma_f32 v[2:3], v[52:53], v[2:3], v[8:9]
	v_lshlrev_b32_e32 v8, 16, v4
	v_and_b32_e32 v9, 0xffff0000, v4
	v_lshlrev_b32_e32 v4, 16, v5
	v_and_b32_e32 v5, 0xffff0000, v5
	v_pk_fma_f32 v[8:9], v[54:55], v[8:9], v[70:71]
	v_pk_fma_f32 v[66:67], v[56:57], v[4:5], v[66:67]
	v_cvt_pk_bf16_f32 v4, v6, v7
	v_cvt_pk_bf16_f32 v5, v2, v3
	v_cvt_pk_bf16_f32 v6, v8, v9
	v_and_or_b32 v0, v213, 64, v202
	v_cvt_pk_bf16_f32 v7, v66, v67
	ds_write_b128 v229, v[4:7] offset:816
	ds_read_b128 v[118:121], v230
	ds_read_b128 v[90:93], v230 offset:64
	ds_read_b128 v[6:9], v230 offset:128
	ds_read_b128 v[2:5], v230 offset:192
	ds_read_b128 v[66:69], v231
	ds_read_b128 v[70:73], v231 offset:34816
	ds_read_b128 v[74:77], v231 offset:64
	ds_read_b128 v[78:81], v231 offset:34880
	ds_read_b128 v[184:187], v231 offset:128
	ds_read_b128 v[188:191], v231 offset:34944
	ds_read_b128 v[192:195], v231 offset:192
	ds_read_b128 v[196:199], v231 offset:35008
	s_waitcnt lgkmcnt(7)
	v_mfma_f32_16x16x32_bf16 v[66:69], v[118:121], v[66:69], 0
	v_lshlrev_b32_e32 v0, 2, v0
	s_waitcnt lgkmcnt(6)
	v_mfma_f32_16x16x32_bf16 v[70:73], v[118:121], v[70:73], 0
	s_waitcnt lgkmcnt(5)
	v_mfma_f32_16x16x32_bf16 v[66:69], v[90:93], v[74:77], v[66:69]
	s_waitcnt lgkmcnt(4)
	v_mfma_f32_16x16x32_bf16 v[70:73], v[90:93], v[78:81], v[70:73]
	s_waitcnt lgkmcnt(3)
	v_mfma_f32_16x16x32_bf16 v[66:69], v[6:9], v[184:187], v[66:69]
	s_waitcnt lgkmcnt(2)
	v_mfma_f32_16x16x32_bf16 v[70:73], v[6:9], v[188:191], v[70:73]
	s_waitcnt lgkmcnt(1)
	v_mfma_f32_16x16x32_bf16 v[134:137], v[2:5], v[192:195], v[66:69]
	s_waitcnt lgkmcnt(0)
	v_mfma_f32_16x16x32_bf16 v[130:133], v[2:5], v[196:199], v[70:73]
	s_nop 0
	ds_read_b128 v[66:69], v231 offset:4352
	s_nop 0
	ds_read_b128 v[70:73], v231 offset:39168
	ds_read_b128 v[74:77], v231 offset:4416
	ds_read_b128 v[78:81], v231 offset:39232
	ds_read_b128 v[184:187], v231 offset:4480
	ds_read_b128 v[188:191], v231 offset:39296
	ds_read_b128 v[192:195], v231 offset:4544
	ds_read_b128 v[196:199], v231 offset:39360
	v_add_f32_e32 v134, v158, v134
	s_waitcnt lgkmcnt(7)
; #define LAS __attribute__((address_space(3)))
; template <int PASS> __device__ __forceinline__ void lru_wave_item(LAS unsigned char* lds, LAS unsigned char* vw, int b, int c, int h, const MixP& p, int lane, float (&Hrun)[8], bool cont) {
;     ...
;         {
; #pragma unroll
;             for (int kk = 0; kk < 4; ++kk) af[kk] = *(const LAS bf16x8*)(vw + fr * WROW + kk * 64 + fq * 16);
; #pragma unroll
;             for (int n = 0; n < 8; ++n) {
;                 aR[n] = (f32x4){0.f, 0.f, 0.f, 0.f}; aI[n] = (f32x4){0.f, 0.f, 0.f, 0.f};
; #pragma unroll
;                 for (int kk = 0; kk < 4; ++kk) {
;                     const bf16x8 ba = *(const LAS bf16x8*)(lds + WA_OFF + (16 * n + fr) * WROW + kk * 64 + fq * 16);
;                     const bf16x8 bx = *(const LAS bf16x8*)(lds + WX_OFF + (16 * n + fr) * WROW + kk * 64 + fq * 16);
;                     aR[n] = __builtin_amdgcn_mfma_f32_16x16x32_bf16(af[kk], ba, aR[n], 0, 0, 0);
;                     aI[n] = __builtin_amdgcn_mfma_f32_16x16x32_bf16(af[kk], bx, aI[n], 0, 0, 0);
;                 }
;             }
	v_mfma_f32_16x16x32_bf16 v[66:69], v[118:121], v[66:69], 0
	v_add_f32_e32 v135, v158, v135
	v_mul_f32_e32 v134, 0xbfb8aa3b, v134
	v_mul_f32_e32 v135, 0xbfb8aa3b, v135
	s_waitcnt lgkmcnt(6)
	v_mfma_f32_16x16x32_bf16 v[70:73], v[118:121], v[70:73], 0
	v_exp_f32_e32 v134, v134
	v_exp_f32_e32 v135, v135
	v_add_f32_e32 v130, v160, v130
	s_waitcnt lgkmcnt(5)
	v_mfma_f32_16x16x32_bf16 v[66:69], v[90:93], v[74:77], v[66:69]
	v_add_f32_e32 v134, 1.0, v134
	v_add_f32_e32 v135, 1.0, v135
	v_rcp_f32_e32 v134, v134
	s_waitcnt lgkmcnt(4)
	v_mfma_f32_16x16x32_bf16 v[70:73], v[90:93], v[78:81], v[70:73]
	v_rcp_f32_e32 v135, v135
	v_mul_f32_e32 v134, v162, v134
	s_waitcnt lgkmcnt(3)
	v_mfma_f32_16x16x32_bf16 v[66:69], v[6:9], v[184:187], v[66:69]
	v_add_f32_e32 v131, v160, v131
	v_mul_f32_e32 v135, v162, v135
	v_mul_f32_e32 v130, 0xbfb8aa3b, v130
	s_waitcnt lgkmcnt(2)
	v_mfma_f32_16x16x32_bf16 v[70:73], v[6:9], v[188:191], v[70:73]
	v_exp_f32_e32 v236, v134
	v_mul_f32_e32 v131, 0xbfb8aa3b, v131
	s_waitcnt lgkmcnt(1)
	v_mfma_f32_16x16x32_bf16 v[126:129], v[2:5], v[192:195], v[66:69]
	v_exp_f32_e32 v130, v130
	v_exp_f32_e32 v131, v131
	v_fma_f32 v134, -v236, v236, 1.0
	s_waitcnt lgkmcnt(0)
	v_mfma_f32_16x16x32_bf16 v[122:125], v[2:5], v[196:199], v[70:73]
	ds_read_b128 v[66:69], v231 offset:8704
	s_nop 1
	ds_read_b128 v[70:73], v231 offset:43520
	ds_read_b128 v[74:77], v231 offset:8768
	ds_read_b128 v[78:81], v231 offset:43584
	ds_read_b128 v[184:187], v231 offset:8832
	ds_read_b128 v[188:191], v231 offset:43648
	ds_read_b128 v[192:195], v231 offset:8896
	ds_read_b128 v[196:199], v231 offset:43712
	v_add_f32_e32 v130, 1.0, v130
	s_waitcnt lgkmcnt(7)
	v_mfma_f32_16x16x32_bf16 v[66:69], v[118:121], v[66:69], 0
	v_max_f32_e32 v134, 0, v134
	v_add_f32_e32 v131, 1.0, v131
	v_rcp_f32_e32 v130, v130
	s_waitcnt lgkmcnt(6)
	v_mfma_f32_16x16x32_bf16 v[70:73], v[118:121], v[70:73], 0
	v_sqrt_f32_e32 v134, v134
	v_rcp_f32_e32 v131, v131
	v_add_f32_e32 v133, v160, v133
	s_waitcnt lgkmcnt(5)
	v_mfma_f32_16x16x32_bf16 v[66:69], v[90:93], v[74:77], v[66:69]
	v_mul_f32_e32 v133, 0xbfb8aa3b, v133
	v_exp_f32_e32 v133, v133
	v_add_f32_e32 v132, v160, v132
	s_waitcnt lgkmcnt(4)
	v_mfma_f32_16x16x32_bf16 v[70:73], v[90:93], v[78:81], v[70:73]
	v_mul_f32_e32 v132, 0xbfb8aa3b, v132
	v_exp_f32_e32 v132, v132
	s_waitcnt lgkmcnt(3)
	v_mfma_f32_16x16x32_bf16 v[66:69], v[6:9], v[184:187], v[66:69]
	v_add_f32_e32 v133, 1.0, v133
	v_add_f32_e32 v132, 1.0, v132
	v_rcp_f32_e32 v132, v132
	s_waitcnt lgkmcnt(2)
	v_mfma_f32_16x16x32_bf16 v[70:73], v[6:9], v[188:191], v[70:73]
	s_waitcnt lgkmcnt(1)
	v_mfma_f32_16x16x32_bf16 v[114:117], v[2:5], v[192:195], v[66:69]
	s_waitcnt lgkmcnt(0)
	v_mfma_f32_16x16x32_bf16 v[110:113], v[2:5], v[196:199], v[70:73]
	s_nop 0
	ds_read_b128 v[66:69], v232
	s_nop 0
	ds_read_b128 v[70:73], v232 offset:34816
	ds_read_b128 v[74:77], v232 offset:64
	ds_read_b128 v[78:81], v232 offset:34880
	ds_read_b128 v[184:187], v232 offset:128
	ds_read_b128 v[188:191], v232 offset:34944
	ds_read_b128 v[192:195], v232 offset:192
	ds_read_b128 v[196:199], v232 offset:35008
	s_waitcnt lgkmcnt(7)
	v_mfma_f32_16x16x32_bf16 v[66:69], v[118:121], v[66:69], 0
	s_waitcnt lgkmcnt(6)
	v_mfma_f32_16x16x32_bf16 v[70:73], v[118:121], v[70:73], 0
	s_waitcnt lgkmcnt(5)
	v_mfma_f32_16x16x32_bf16 v[66:69], v[90:93], v[74:77], v[66:69]
	s_waitcnt lgkmcnt(4)
	v_mfma_f32_16x16x32_bf16 v[70:73], v[90:93], v[78:81], v[70:73]
	s_waitcnt lgkmcnt(3)
	v_mfma_f32_16x16x32_bf16 v[66:69], v[6:9], v[184:187], v[66:69]
	s_waitcnt lgkmcnt(2)
	v_mfma_f32_16x16x32_bf16 v[70:73], v[6:9], v[188:191], v[70:73]
	s_waitcnt lgkmcnt(1)
	v_mfma_f32_16x16x32_bf16 v[106:109], v[2:5], v[192:195], v[66:69]
	s_waitcnt lgkmcnt(0)
	v_mfma_f32_16x16x32_bf16 v[102:105], v[2:5], v[196:199], v[70:73]
	s_nop 0
	ds_read_b128 v[66:69], v231 offset:17408
	s_nop 0
	ds_read_b128 v[70:73], v231 offset:52224
	ds_read_b128 v[74:77], v231 offset:17472
	ds_read_b128 v[78:81], v231 offset:52288
	ds_read_b128 v[184:187], v231 offset:17536
	ds_read_b128 v[188:191], v231 offset:52352
	ds_read_b128 v[192:195], v231 offset:17600
	ds_read_b128 v[196:199], v231 offset:52416
	s_waitcnt lgkmcnt(7)
	v_mfma_f32_16x16x32_bf16 v[66:69], v[118:121], v[66:69], 0
	s_waitcnt lgkmcnt(6)
	v_mfma_f32_16x16x32_bf16 v[70:73], v[118:121], v[70:73], 0
	s_waitcnt lgkmcnt(5)
	v_mfma_f32_16x16x32_bf16 v[66:69], v[90:93], v[74:77], v[66:69]
	s_waitcnt lgkmcnt(4)
	v_mfma_f32_16x16x32_bf16 v[70:73], v[90:93], v[78:81], v[70:73]
	s_waitcnt lgkmcnt(3)
	v_mfma_f32_16x16x32_bf16 v[66:69], v[6:9], v[184:187], v[66:69]
	s_waitcnt lgkmcnt(2)
	v_mfma_f32_16x16x32_bf16 v[70:73], v[6:9], v[188:191], v[70:73]
	s_waitcnt lgkmcnt(1)
	v_mfma_f32_16x16x32_bf16 v[98:101], v[2:5], v[192:195], v[66:69]
	s_waitcnt lgkmcnt(0)
	v_mfma_f32_16x16x32_bf16 v[94:97], v[2:5], v[196:199], v[70:73]
	s_nop 0
	ds_read_b128 v[66:69], v231 offset:21760
	s_nop 0
	ds_read_b128 v[70:73], v231 offset:56576
	ds_read_b128 v[74:77], v231 offset:21824
	ds_read_b128 v[78:81], v231 offset:56640
	ds_read_b128 v[184:187], v231 offset:21888
	ds_read_b128 v[188:191], v231 offset:56704
	ds_read_b128 v[192:195], v231 offset:21952
	ds_read_b128 v[196:199], v231 offset:56768
	s_waitcnt lgkmcnt(7)
	v_mfma_f32_16x16x32_bf16 v[66:69], v[118:121], v[66:69], 0
	s_waitcnt lgkmcnt(6)
	v_mfma_f32_16x16x32_bf16 v[70:73], v[118:121], v[70:73], 0
	s_waitcnt lgkmcnt(5)
	v_mfma_f32_16x16x32_bf16 v[66:69], v[90:93], v[74:77], v[66:69]
	s_waitcnt lgkmcnt(4)
	v_mfma_f32_16x16x32_bf16 v[70:73], v[90:93], v[78:81], v[70:73]
	s_waitcnt lgkmcnt(3)
	v_mfma_f32_16x16x32_bf16 v[66:69], v[6:9], v[184:187], v[66:69]
	s_waitcnt lgkmcnt(2)
; #define LAS __attribute__((address_space(3)))
; __device__ __forceinline__ float fsig2(float x) { return __builtin_amdgcn_rcpf(1.0f + __builtin_amdgcn_exp2f(-LOG2E * x)); }
; template <int PASS> __device__ __forceinline__ void lru_wave_item(LAS unsigned char* lds, LAS unsigned char* vw, int b, int c, int h, const MixP& p, int lane, float (&Hrun)[8], bool cont) {
;     ...
;         {
; #pragma unroll
;             for (int kk = 0; kk < 4; ++kk) af[kk] = *(const LAS bf16x8*)(vw + fr * WROW + kk * 64 + fq * 16);
; #pragma unroll
;             for (int n = 0; n < 8; ++n) {
;                 aR[n] = (f32x4){0.f, 0.f, 0.f, 0.f}; aI[n] = (f32x4){0.f, 0.f, 0.f, 0.f};
; #pragma unroll
;                 for (int kk = 0; kk < 4; ++kk) {
;                     const bf16x8 ba = *(const LAS bf16x8*)(lds + WA_OFF + (16 * n + fr) * WROW + kk * 64 + fq * 16);
;                     const bf16x8 bx = *(const LAS bf16x8*)(lds + WX_OFF + (16 * n + fr) * WROW + kk * 64 + fq * 16);
;                     aR[n] = __builtin_amdgcn_mfma_f32_16x16x32_bf16(af[kk], ba, aR[n], 0, 0, 0);
;                     aI[n] = __builtin_amdgcn_mfma_f32_16x16x32_bf16(af[kk], bx, aI[n], 0, 0, 0);
;                 }
;             }
;         }
; #pragma unroll
;         for (int n = 0; n < 8; ++n) {
;             const f32x4 aVn = __builtin_amdgcn_mfma_f32_16x16x32_bf16(af[n >> 1], idf[n & 1], (f32x4){0.f, 0.f, 0.f, 0.f}, 0, 0, 0);
;             float av[4], bxv[4];
; #pragma unroll
;             for (int j = 0; j < 4; ++j) {
;                 const float r = fsig2(aR[n][j] + pba[n]), ig = fsig2(aI[n][j] + pbx[n]);
;                 const float a = __builtin_amdgcn_exp2f(r * pk8[n]), mult = __builtin_amdgcn_sqrtf(fmaxf(1.0f - a * a, 0.f));
	v_mfma_f32_16x16x32_bf16 v[70:73], v[6:9], v[188:191], v[70:73]
	s_waitcnt lgkmcnt(1)
	v_mfma_f32_16x16x32_bf16 v[86:89], v[2:5], v[192:195], v[66:69]
	s_waitcnt lgkmcnt(0)
	v_mfma_f32_16x16x32_bf16 v[82:85], v[2:5], v[196:199], v[70:73]
	s_nop 0
	ds_read_b128 v[66:69], v231 offset:26112
	s_nop 0
	ds_read_b128 v[70:73], v231 offset:60928
	ds_read_b128 v[74:77], v231 offset:26176
	ds_read_b128 v[78:81], v231 offset:60992
	v_add_f32_e32 v86, v171, v86
	s_waitcnt lgkmcnt(3)
	v_mfma_f32_16x16x32_bf16 v[66:69], v[118:121], v[66:69], 0
	v_add_f32_e32 v87, v171, v87
	v_mul_f32_e32 v86, 0xbfb8aa3b, v86
	v_mul_f32_e32 v87, 0xbfb8aa3b, v87
	s_waitcnt lgkmcnt(2)
	v_mfma_f32_16x16x32_bf16 v[70:73], v[118:121], v[70:73], 0
	v_exp_f32_e32 v86, v86
	v_exp_f32_e32 v87, v87
	v_add_f32_e32 v82, v173, v82
	s_waitcnt lgkmcnt(1)
	v_mfma_f32_16x16x32_bf16 v[66:69], v[90:93], v[74:77], v[66:69]
	v_add_f32_e32 v86, 1.0, v86
	v_add_f32_e32 v87, 1.0, v87
	v_rcp_f32_e32 v86, v86
	s_waitcnt lgkmcnt(0)
	v_mfma_f32_16x16x32_bf16 v[70:73], v[90:93], v[78:81], v[70:73]
	ds_read_b128 v[74:77], v231 offset:26240
	ds_read_b128 v[78:81], v231 offset:61056
	v_rcp_f32_e32 v87, v87
	v_mul_f32_e32 v86, v175, v86
	s_waitcnt lgkmcnt(1)
	v_mfma_f32_16x16x32_bf16 v[66:69], v[6:9], v[74:77], v[66:69]
	ds_read_b128 v[74:77], v231 offset:26304
	ds_read_b128 v[138:141], v231 offset:61120
	v_add_f32_e32 v83, v173, v83
	v_mul_f32_e32 v87, v175, v87
	s_waitcnt lgkmcnt(2)
	v_mfma_f32_16x16x32_bf16 v[70:73], v[6:9], v[78:81], v[70:73]
	v_mul_f32_e32 v82, 0xbfb8aa3b, v82
	v_mul_f32_e32 v83, 0xbfb8aa3b, v83
	v_exp_f32_e32 v82, v82
	s_waitcnt lgkmcnt(1)
	v_mfma_f32_16x16x32_bf16 v[78:81], v[2:5], v[74:77], v[66:69]
	v_exp_f32_e32 v83, v83
	v_add_f32_e32 v85, v173, v85
	v_add_f32_e32 v82, 1.0, v82
	s_waitcnt lgkmcnt(0)
	v_mfma_f32_16x16x32_bf16 v[74:77], v[2:5], v[138:141], v[70:73]
	ds_read_b128 v[66:69], v233
	s_nop 1
	ds_read_b128 v[70:73], v233 offset:34816
	ds_read_b128 v[138:141], v233 offset:64
	ds_read_b128 v[184:187], v233 offset:34880
	v_add_f32_e32 v83, 1.0, v83
	s_waitcnt lgkmcnt(3)
	v_mfma_f32_16x16x32_bf16 v[66:69], v[118:121], v[66:69], 0
	v_rcp_f32_e32 v82, v82
	v_rcp_f32_e32 v83, v83
	v_mul_f32_e32 v85, 0xbfb8aa3b, v85
	s_waitcnt lgkmcnt(2)
	v_mfma_f32_16x16x32_bf16 v[70:73], v[118:121], v[70:73], 0
	v_exp_f32_e32 v85, v85
	s_nop 0
	v_add_f32_e32 v85, 1.0, v85
	s_waitcnt lgkmcnt(1)
	v_mfma_f32_16x16x32_bf16 v[66:69], v[90:93], v[138:141], v[66:69]
	s_waitcnt lgkmcnt(0)
	v_mfma_f32_16x16x32_bf16 v[70:73], v[90:93], v[184:187], v[70:73]
	ds_read_b128 v[138:141], v233 offset:128
	ds_read_b128 v[184:187], v233 offset:34944
	s_waitcnt lgkmcnt(1)
	v_mfma_f32_16x16x32_bf16 v[66:69], v[6:9], v[138:141], v[66:69]
	s_waitcnt lgkmcnt(0)
	v_mfma_f32_16x16x32_bf16 v[138:141], v[6:9], v[184:187], v[70:73]
	s_nop 2
	ds_read_b128 v[70:73], v233 offset:192
	ds_read_b128 v[184:187], v233 offset:35008
	s_waitcnt lgkmcnt(1)
	v_mfma_f32_16x16x32_bf16 v[70:73], v[2:5], v[70:73], v[66:69]
	s_waitcnt lgkmcnt(0)
	v_mfma_f32_16x16x32_bf16 v[66:69], v[2:5], v[184:187], v[138:141]
	v_exp_f32_e32 v186, v135
	s_nop 0
	v_fma_f32 v135, -v186, v186, 1.0
	v_max_f32_e32 v135, 0, v135
	v_sqrt_f32_e32 v135, v135
	v_mfma_f32_16x16x32_bf16 v[138:141], v[118:121], v[18:21], 0
	s_nop 1
	v_add_f32_e32 v66, v179, v66
	v_add_f32_e32 v67, v179, v67
	v_pk_mul_f32 v[130:131], v[130:131], v[134:135]
	v_add_f32_e32 v134, v158, v136
	v_mul_f32_e32 v134, 0xbfb8aa3b, v134
	v_exp_f32_e32 v134, v134
	v_pk_mul_f32 v[130:131], v[130:131], v[138:139]
	v_rcp_f32_e32 v136, v133
	v_mul_f32_e32 v66, 0xbfb8aa3b, v66
	v_add_f32_e32 v134, 1.0, v134
	v_rcp_f32_e32 v134, v134
	v_mul_f32_e32 v67, 0xbfb8aa3b, v67
	v_exp_f32_e32 v66, v66
	v_exp_f32_e32 v67, v67
	v_mul_f32_e32 v134, v162, v134
	v_exp_f32_e32 v139, v134
	v_add_f32_e32 v134, v158, v137
	v_mul_f32_e32 v134, 0xbfb8aa3b, v134
	v_exp_f32_e32 v134, v134
	v_add_f32_e32 v66, 1.0, v66
	v_add_f32_e32 v67, 1.0, v67
	v_rcp_f32_e32 v66, v66
	v_add_f32_e32 v134, 1.0, v134
	v_rcp_f32_e32 v134, v134
	v_rcp_f32_e32 v67, v67
	v_add_f32_e32 v69, v179, v69
	v_mul_f32_e32 v69, 0xbfb8aa3b, v69
	v_mul_f32_e32 v133, v162, v134
	v_exp_f32_e32 v185, v133
	v_fma_f32 v133, v186, v130, v131
	v_fma_f32 v131, -v139, v139, 1.0
	v_max_f32_e32 v131, 0, v131
	v_sqrt_f32_e32 v138, v131
	v_fma_f32 v131, -v185, v185, 1.0
	v_max_f32_e32 v131, 0, v131
	v_sqrt_f32_e32 v184, v131
	v_pk_mul_f32 v[134:135], v[132:133], v[138:139]
	v_mul_f32_e32 v131, v186, v236
	v_fmac_f32_e32 v135, v134, v140
	v_mov_b32_e32 v137, v135
	v_pk_mul_f32 v[136:137], v[136:137], v[184:185]
	v_mul_f32_e32 v132, v139, v131
	v_fmac_f32_e32 v137, v136, v141
	v_mfma_f32_16x16x32_bf16 v[138:141], v[118:121], v[22:25], 0
	v_add_f32_e32 v118, v159, v126
	v_mul_f32_e32 v118, 0xbfb8aa3b, v118
	v_exp_f32_e32 v118, v118
	v_mul_f32_e32 v134, v185, v132
	ds_bpermute_b32 v188, v0, v134
	ds_bpermute_b32 v192, v0, v137
	v_add_f32_e32 v118, 1.0, v118
	v_rcp_f32_e32 v119, v118
	v_add_f32_e32 v118, v161, v122
	v_mul_f32_e32 v118, 0xbfb8aa3b, v118
	v_exp_f32_e32 v118, v118
	v_mul_f32_e32 v119, v163, v119
	v_exp_f32_e32 v136, v119
	v_add_f32_e32 v122, v161, v125
	v_add_f32_e32 v118, 1.0, v118
	v_rcp_f32_e32 v118, v118
	v_fma_f32 v119, -v136, v136, 1.0
	v_max_f32_e32 v119, 0, v119
	v_sqrt_f32_e32 v120, v119
	v_add_f32_e32 v119, v159, v127
	v_mul_f32_e32 v119, 0xbfb8aa3b, v119
	v_exp_f32_e32 v119, v119
	v_mul_f32_e32 v122, 0xbfb8aa3b, v122
	v_exp_f32_e32 v122, v122
	ds_bpermute_b32 v190, v0, v134 offset:64
	v_add_f32_e32 v119, 1.0, v119
	v_rcp_f32_e32 v121, v119
	v_add_f32_e32 v119, v161, v123
	v_mul_f32_e32 v119, 0xbfb8aa3b, v119
	v_exp_f32_e32 v119, v119
; __device__ __forceinline__ float fsig2(float x) { return __builtin_amdgcn_rcpf(1.0f + __builtin_amdgcn_exp2f(-LOG2E * x)); }
; template <int PASS> __device__ __forceinline__ void lru_wave_item(LAS unsigned char* lds, LAS unsigned char* vw, int b, int c, int h, const MixP& p, int lane, float (&Hrun)[8], bool cont) {
;     ...
;         for (int n = 0; n < 8; ++n) {
;             const f32x4 aVn = __builtin_amdgcn_mfma_f32_16x16x32_bf16(af[n >> 1], idf[n & 1], (f32x4){0.f, 0.f, 0.f, 0.f}, 0, 0, 0);
;             float av[4], bxv[4];
; #pragma unroll
;             for (int j = 0; j < 4; ++j) {
;                 const float r = fsig2(aR[n][j] + pba[n]), ig = fsig2(aI[n][j] + pbx[n]);
;                 const float a = __builtin_amdgcn_exp2f(r * pk8[n]), mult = __builtin_amdgcn_sqrtf(fmaxf(1.0f - a * a, 0.f));
;                 av[j] = a; bxv[j] = mult * ig * aVn[j];
;             }
;             const float H0 = bxv[0], H1 = av[1] * H0 + bxv[1], H2 = av[2] * H1 + bxv[2], H3 = av[3] * H2 + bxv[3];
;             const float A0 = av[0], A1 = av[1] * A0, A2 = av[2] * A1, A3 = av[3] * A2;
;             float At[4], Ht[4];
; #pragma unroll
;             for (int q = 0; q < 4; ++q) { At[q] = __shfl(A3, fr + 16 * q); Ht[q] = __shfl(H3, fr + 16 * q); }
;             const float c0 = Hrun[n], c1 = At[0] * c0 + Ht[0], c2 = At[1] * c1 + Ht[1], c3 = At[2] * c2 + Ht[2], c4 = At[3] * c3 + Ht[3];
;             Hrun[n] = c4;
;             if (PASS == 1) Arun[n] *= (At[0] * At[1]) * (At[2] * At[3]);
;             if (PASS == 2) {
;                 const float cin = fq == 0 ? c0 : (fq == 1 ? c1 : (fq == 2 ? c2 : c3));
;                 aR[n][0] = H0 + A0 * cin; aR[n][1] = H1 + A1 * cin; aR[n][2] = H2 + A2 * cin; aR[n][3] = H3 + A3 * cin;
;             }
	v_mul_f32_e32 v121, v163, v121
	v_exp_f32_e32 v185, v121
	v_add_f32_e32 v122, 1.0, v122
	v_add_f32_e32 v119, 1.0, v119
	v_rcp_f32_e32 v119, v119
	v_fma_f32 v121, -v185, v185, 1.0
	v_max_f32_e32 v121, 0, v121
	v_sqrt_f32_e32 v121, v121
	ds_bpermute_b32 v196, v0, v137 offset:64
	ds_bpermute_b32 v194, v0, v134 offset:128
	ds_bpermute_b32 v198, v0, v137 offset:128
	v_pk_mul_f32 v[118:119], v[118:119], v[120:121]
	v_add_f32_e32 v120, v159, v128
	v_mul_f32_e32 v120, 0xbfb8aa3b, v120
	v_exp_f32_e32 v120, v120
	v_pk_mul_f32 v[118:119], v[118:119], v[138:139]
	ds_bpermute_b32 v186, v0, v137 offset:192
	v_exp_f32_e32 v69, v69
	v_add_f32_e32 v120, 1.0, v120
	v_rcp_f32_e32 v121, v120
	v_add_f32_e32 v120, v161, v124
	v_mul_f32_e32 v120, 0xbfb8aa3b, v120
	v_exp_f32_e32 v120, v120
	v_mul_f32_e32 v121, v163, v121
	v_exp_f32_e32 v127, v121
	v_add_f32_e32 v121, v159, v129
	v_mul_f32_e32 v121, 0xbfb8aa3b, v121
	v_exp_f32_e32 v121, v121
	v_add_f32_e32 v120, 1.0, v120
	v_rcp_f32_e32 v120, v120
	v_rcp_f32_e32 v124, v122
	v_add_f32_e32 v121, 1.0, v121
	v_rcp_f32_e32 v121, v121
	v_add_f32_e32 v69, 1.0, v69
	ds_bpermute_b32 v184, v0, v134 offset:192
	v_mul_f32_e32 v121, v163, v121
	v_exp_f32_e32 v129, v121
	v_fma_f32 v121, v185, v118, v119
	v_fma_f32 v119, -v127, v127, 1.0
	v_max_f32_e32 v119, 0, v119
	v_sqrt_f32_e32 v126, v119
	v_fma_f32 v119, -v129, v129, 1.0
	v_max_f32_e32 v119, 0, v119
	v_sqrt_f32_e32 v128, v119
	v_pk_mul_f32 v[122:123], v[120:121], v[126:127]
	v_mul_f32_e32 v119, v185, v136
	v_fmac_f32_e32 v123, v122, v140
	v_mov_b32_e32 v125, v123
	v_pk_mul_f32 v[124:125], v[124:125], v[128:129]
	v_mul_f32_e32 v120, v127, v119
	v_fmac_f32_e32 v125, v124, v141
	v_mul_f32_e32 v122, v129, v120
	ds_bpermute_b32 v189, v0, v122
	ds_bpermute_b32 v193, v0, v125
	ds_bpermute_b32 v191, v0, v122 offset:64
	ds_bpermute_b32 v197, v0, v125 offset:64
	ds_bpermute_b32 v195, v0, v122 offset:128
	ds_bpermute_b32 v199, v0, v125 offset:128
	s_waitcnt lgkmcnt(4)
	v_pk_fma_f32 v[128:129], v[10:11], v[188:189], v[192:193]
	ds_bpermute_b32 v187, v0, v125 offset:192
	s_waitcnt lgkmcnt(3)
	v_pk_fma_f32 v[138:139], v[128:129], v[190:191], v[196:197]
	ds_bpermute_b32 v185, v0, v122 offset:192
	s_waitcnt lgkmcnt(2)
	v_pk_fma_f32 v[126:127], v[138:139], v[194:195], v[198:199]
	s_nop 0
	v_cndmask_b32_e64 v124, v126, v138, s[8:9]
	v_cndmask_b32_e64 v124, v124, v128, s[6:7]
	v_cndmask_b32_e64 v10, v124, v10, s[4:5]
	v_fmac_f32_e32 v130, v236, v10
	v_fmac_f32_e32 v133, v131, v10
	v_fmac_f32_e32 v135, v132, v10
	v_fmac_f32_e32 v137, v134, v10
	v_cndmask_b32_e64 v10, v127, v139, s[8:9]
	v_cndmask_b32_e64 v10, v10, v129, s[6:7]
	v_cndmask_b32_e64 v10, v10, v11, s[4:5]
	v_fmac_f32_e32 v118, v136, v10
	v_fmac_f32_e32 v121, v119, v10
	v_fmac_f32_e32 v123, v120, v10
	v_fmac_f32_e32 v125, v122, v10
	v_add_f32_e32 v10, v164, v114
	v_mul_f32_e32 v10, 0xbfb8aa3b, v10
	v_exp_f32_e32 v10, v10
	v_mfma_f32_16x16x32_bf16 v[138:141], v[90:93], v[18:21], 0
	v_add_f32_e32 v10, 1.0, v10
	v_rcp_f32_e32 v11, v10
	v_add_f32_e32 v10, v166, v110
	v_mul_f32_e32 v10, 0xbfb8aa3b, v10
	v_exp_f32_e32 v10, v10
	v_mul_f32_e32 v11, v168, v11
	v_exp_f32_e32 v119, v11
	v_add_f32_e32 v10, 1.0, v10
	v_rcp_f32_e32 v10, v10
	v_fma_f32 v11, -v119, v119, 1.0
	v_max_f32_e32 v11, 0, v11
	v_sqrt_f32_e32 v110, v11
	v_add_f32_e32 v11, v164, v115
	v_mul_f32_e32 v11, 0xbfb8aa3b, v11
	v_exp_f32_e32 v11, v11
	s_nop 0
	v_add_f32_e32 v11, 1.0, v11
	v_rcp_f32_e32 v114, v11
	v_add_f32_e32 v11, v166, v111
	v_mul_f32_e32 v11, 0xbfb8aa3b, v11
	v_exp_f32_e32 v11, v11
	v_mul_f32_e32 v111, v168, v114
	v_exp_f32_e32 v120, v111
	v_add_f32_e32 v11, 1.0, v11
	v_rcp_f32_e32 v11, v11
	v_fma_f32 v111, -v120, v120, 1.0
	v_max_f32_e32 v111, 0, v111
	v_sqrt_f32_e32 v111, v111
	s_nop 0
	v_pk_mul_f32 v[10:11], v[10:11], v[110:111]
	v_add_f32_e32 v110, v164, v116
	v_mul_f32_e32 v110, 0xbfb8aa3b, v110
	v_exp_f32_e32 v110, v110
	v_pk_mul_f32 v[10:11], v[10:11], v[138:139]
	v_add_f32_e32 v110, 1.0, v110
	v_rcp_f32_e32 v111, v110
	v_add_f32_e32 v110, v166, v112
	v_mul_f32_e32 v110, 0xbfb8aa3b, v110
	v_exp_f32_e32 v110, v110
	v_mul_f32_e32 v111, v168, v111
	v_exp_f32_e32 v129, v111
	v_add_f32_e32 v111, v164, v117
	v_mul_f32_e32 v111, 0xbfb8aa3b, v111
	v_exp_f32_e32 v111, v111
	v_add_f32_e32 v112, v166, v113
	v_mul_f32_e32 v112, 0xbfb8aa3b, v112
	v_exp_f32_e32 v112, v112
	v_add_f32_e32 v111, 1.0, v111
	v_rcp_f32_e32 v111, v111
	v_add_f32_e32 v110, 1.0, v110
	v_rcp_f32_e32 v110, v110
	v_add_f32_e32 v112, 1.0, v112
	v_mul_f32_e32 v111, v168, v111
	v_exp_f32_e32 v117, v111
	v_fma_f32 v111, v120, v10, v11
	v_fma_f32 v11, -v129, v129, 1.0
	v_max_f32_e32 v11, 0, v11
	v_sqrt_f32_e32 v128, v11
	v_fma_f32 v11, -v117, v117, 1.0
	v_max_f32_e32 v11, 0, v11
	v_rcp_f32_e32 v114, v112
	v_sqrt_f32_e32 v116, v11
	v_pk_mul_f32 v[112:113], v[110:111], v[128:129]
	v_mul_f32_e32 v11, v120, v119
	v_fmac_f32_e32 v113, v112, v140
	v_mov_b32_e32 v115, v113
	v_pk_mul_f32 v[114:115], v[114:115], v[116:117]
	v_mul_f32_e32 v110, v129, v11
	v_fmac_f32_e32 v115, v114, v141
	v_mfma_f32_16x16x32_bf16 v[138:141], v[90:93], v[22:25], 0
	v_add_f32_e32 v90, v165, v106
	v_mul_f32_e32 v90, 0xbfb8aa3b, v90
	v_exp_f32_e32 v90, v90
	v_mul_f32_e32 v112, v117, v110
	ds_bpermute_b32 v188, v0, v112
	ds_bpermute_b32 v190, v0, v115
	v_add_f32_e32 v90, 1.0, v90
	v_rcp_f32_e32 v91, v90
	v_add_f32_e32 v90, v167, v102
	v_mul_f32_e32 v90, 0xbfb8aa3b, v90
	v_exp_f32_e32 v90, v90
	v_mul_f32_e32 v91, v169, v91
	v_exp_f32_e32 v114, v91
	v_add_f32_e32 v102, v167, v105
	v_add_f32_e32 v90, 1.0, v90
	v_rcp_f32_e32 v90, v90
	v_fma_f32 v91, -v114, v114, 1.0
	v_max_f32_e32 v91, 0, v91
	v_sqrt_f32_e32 v92, v91
	v_add_f32_e32 v91, v165, v107
; __device__ __forceinline__ float fsig2(float x) { return __builtin_amdgcn_rcpf(1.0f + __builtin_amdgcn_exp2f(-LOG2E * x)); }
; template <int PASS> __device__ __forceinline__ void lru_wave_item(LAS unsigned char* lds, LAS unsigned char* vw, int b, int c, int h, const MixP& p, int lane, float (&Hrun)[8], bool cont) {
;     ...
;         for (int n = 0; n < 8; ++n) {
;             const f32x4 aVn = __builtin_amdgcn_mfma_f32_16x16x32_bf16(af[n >> 1], idf[n & 1], (f32x4){0.f, 0.f, 0.f, 0.f}, 0, 0, 0);
;             float av[4], bxv[4];
; #pragma unroll
;             for (int j = 0; j < 4; ++j) {
;                 const float r = fsig2(aR[n][j] + pba[n]), ig = fsig2(aI[n][j] + pbx[n]);
;                 const float a = __builtin_amdgcn_exp2f(r * pk8[n]), mult = __builtin_amdgcn_sqrtf(fmaxf(1.0f - a * a, 0.f));
;                 av[j] = a; bxv[j] = mult * ig * aVn[j];
;             }
;             const float H0 = bxv[0], H1 = av[1] * H0 + bxv[1], H2 = av[2] * H1 + bxv[2], H3 = av[3] * H2 + bxv[3];
;             const float A0 = av[0], A1 = av[1] * A0, A2 = av[2] * A1, A3 = av[3] * A2;
;             float At[4], Ht[4];
; #pragma unroll
;             for (int q = 0; q < 4; ++q) { At[q] = __shfl(A3, fr + 16 * q); Ht[q] = __shfl(H3, fr + 16 * q); }
;             const float c0 = Hrun[n], c1 = At[0] * c0 + Ht[0], c2 = At[1] * c1 + Ht[1], c3 = At[2] * c2 + Ht[2], c4 = At[3] * c3 + Ht[3];
;             Hrun[n] = c4;
;             if (PASS == 1) Arun[n] *= (At[0] * At[1]) * (At[2] * At[3]);
;             if (PASS == 2) {
;                 const float cin = fq == 0 ? c0 : (fq == 1 ? c1 : (fq == 2 ? c2 : c3));
;                 aR[n][0] = H0 + A0 * cin; aR[n][1] = H1 + A1 * cin; aR[n][2] = H2 + A2 * cin; aR[n][3] = H3 + A3 * cin;
;             }
	v_mul_f32_e32 v91, 0xbfb8aa3b, v91
	v_exp_f32_e32 v91, v91
	v_mul_f32_e32 v102, 0xbfb8aa3b, v102
	v_exp_f32_e32 v102, v102
	ds_bpermute_b32 v192, v0, v112 offset:64
	v_add_f32_e32 v91, 1.0, v91
	v_rcp_f32_e32 v93, v91
	v_add_f32_e32 v91, v167, v103
	v_mul_f32_e32 v91, 0xbfb8aa3b, v91
	v_exp_f32_e32 v91, v91
	v_mul_f32_e32 v93, v169, v93
	v_exp_f32_e32 v117, v93
	v_add_f32_e32 v102, 1.0, v102
	v_add_f32_e32 v91, 1.0, v91
	v_rcp_f32_e32 v91, v91
	v_fma_f32 v93, -v117, v117, 1.0
	v_max_f32_e32 v93, 0, v93
	v_sqrt_f32_e32 v93, v93
	ds_bpermute_b32 v194, v0, v115 offset:64
	ds_bpermute_b32 v196, v0, v112 offset:128
	ds_bpermute_b32 v198, v0, v115 offset:128
	v_pk_mul_f32 v[90:91], v[90:91], v[92:93]
	v_add_f32_e32 v92, v165, v108
	v_mul_f32_e32 v92, 0xbfb8aa3b, v92
	v_exp_f32_e32 v92, v92
	v_pk_mul_f32 v[90:91], v[90:91], v[138:139]
	ds_bpermute_b32 v128, v0, v115 offset:192
	ds_bpermute_b32 v116, v0, v112 offset:192
	v_add_f32_e32 v92, 1.0, v92
	v_rcp_f32_e32 v93, v92
	v_add_f32_e32 v92, v167, v104
	v_mul_f32_e32 v92, 0xbfb8aa3b, v92
	v_exp_f32_e32 v92, v92
	v_mul_f32_e32 v93, v169, v93
	v_exp_f32_e32 v107, v93
	v_add_f32_e32 v93, v165, v109
	v_mul_f32_e32 v93, 0xbfb8aa3b, v93
	v_exp_f32_e32 v93, v93
	v_add_f32_e32 v92, 1.0, v92
	v_rcp_f32_e32 v92, v92
	v_rcp_f32_e32 v104, v102
	v_add_f32_e32 v93, 1.0, v93
	v_rcp_f32_e32 v93, v93
	s_nop 0
	v_mul_f32_e32 v93, v169, v93
	v_exp_f32_e32 v109, v93
	v_fma_f32 v93, v117, v90, v91
	v_fma_f32 v91, -v107, v107, 1.0
	v_max_f32_e32 v91, 0, v91
	v_sqrt_f32_e32 v106, v91
	v_fma_f32 v91, -v109, v109, 1.0
	v_max_f32_e32 v91, 0, v91
	v_sqrt_f32_e32 v108, v91
	v_pk_mul_f32 v[102:103], v[92:93], v[106:107]
	v_mul_f32_e32 v91, v117, v114
	v_fmac_f32_e32 v103, v102, v140
	v_mov_b32_e32 v105, v103
	v_pk_mul_f32 v[104:105], v[104:105], v[108:109]
	v_mul_f32_e32 v92, v107, v91
	v_fmac_f32_e32 v105, v104, v141
	v_mul_f32_e32 v102, v109, v92
	ds_bpermute_b32 v189, v0, v102
	ds_bpermute_b32 v191, v0, v105
	ds_bpermute_b32 v193, v0, v102 offset:64
	ds_bpermute_b32 v195, v0, v105 offset:64
	ds_bpermute_b32 v197, v0, v102 offset:128
	ds_bpermute_b32 v199, v0, v105 offset:128
	s_waitcnt lgkmcnt(4)
	v_pk_fma_f32 v[108:109], v[12:13], v[188:189], v[190:191]
	ds_bpermute_b32 v129, v0, v105 offset:192
	s_waitcnt lgkmcnt(3)
	v_pk_fma_f32 v[138:139], v[108:109], v[192:193], v[194:195]
	ds_bpermute_b32 v117, v0, v102 offset:192
	s_waitcnt lgkmcnt(2)
	v_pk_fma_f32 v[106:107], v[138:139], v[196:197], v[198:199]
	s_nop 0
	v_cndmask_b32_e64 v104, v106, v138, s[8:9]
	v_cndmask_b32_e64 v104, v104, v108, s[6:7]
	v_cndmask_b32_e64 v12, v104, v12, s[4:5]
	v_fmac_f32_e32 v111, v11, v12
	v_cndmask_b32_e64 v11, v107, v139, s[8:9]
	v_cndmask_b32_e64 v11, v11, v109, s[6:7]
	v_cndmask_b32_e64 v11, v11, v13, s[4:5]
	v_fmac_f32_e32 v90, v114, v11
	v_fmac_f32_e32 v93, v91, v11
	v_fmac_f32_e32 v103, v92, v11
	v_fmac_f32_e32 v105, v102, v11
	v_add_f32_e32 v11, v170, v98
	v_mul_f32_e32 v11, 0xbfb8aa3b, v11
	v_exp_f32_e32 v11, v11
	v_fmac_f32_e32 v10, v119, v12
	v_fmac_f32_e32 v113, v110, v12
	v_fmac_f32_e32 v115, v112, v12
	v_add_f32_e32 v11, 1.0, v11
	v_rcp_f32_e32 v11, v11
	v_add_f32_e32 v12, v172, v94
	v_mul_f32_e32 v12, 0xbfb8aa3b, v12
	v_exp_f32_e32 v12, v12
	v_mul_f32_e32 v11, v174, v11
	v_exp_f32_e32 v11, v11
	v_mfma_f32_16x16x32_bf16 v[138:141], v[6:9], v[18:21], 0
	v_add_f32_e32 v12, 1.0, v12
	v_rcp_f32_e32 v12, v12
	v_fma_f32 v13, -v11, v11, 1.0
	v_max_f32_e32 v13, 0, v13
	v_sqrt_f32_e32 v94, v13
	v_add_f32_e32 v13, v170, v99
	v_mul_f32_e32 v13, 0xbfb8aa3b, v13
	v_exp_f32_e32 v13, v13
	v_mfma_f32_16x16x32_bf16 v[6:9], v[6:9], v[22:25], 0
	v_add_f32_e32 v13, 1.0, v13
	v_rcp_f32_e32 v91, v13
	v_add_f32_e32 v13, v172, v95
	v_mul_f32_e32 v13, 0xbfb8aa3b, v13
	v_exp_f32_e32 v13, v13
	v_mul_f32_e32 v91, v174, v91
	v_exp_f32_e32 v91, v91
	v_add_f32_e32 v13, 1.0, v13
	v_rcp_f32_e32 v13, v13
	v_fma_f32 v92, -v91, v91, 1.0
	v_max_f32_e32 v92, 0, v92
	v_sqrt_f32_e32 v95, v92
	v_add_f32_e32 v92, v170, v100
	v_mul_f32_e32 v92, 0xbfb8aa3b, v92
	v_exp_f32_e32 v92, v92
	v_pk_mul_f32 v[12:13], v[12:13], v[94:95]
	v_add_f32_e32 v95, v172, v97
	v_mul_f32_e32 v95, 0xbfb8aa3b, v95
	v_add_f32_e32 v92, 1.0, v92
	v_rcp_f32_e32 v92, v92
	v_add_f32_e32 v94, v172, v96
	v_exp_f32_e32 v95, v95
	v_mul_f32_e32 v94, 0xbfb8aa3b, v94
	v_mul_f32_e32 v92, v174, v92
	v_exp_f32_e32 v109, v92
	v_exp_f32_e32 v94, v94
	v_pk_mul_f32 v[12:13], v[12:13], v[138:139]
	v_add_f32_e32 v95, 1.0, v95
	v_rcp_f32_e32 v98, v95
	v_fma_f32 v95, v91, v12, v13
	v_fma_f32 v13, -v109, v109, 1.0
	v_add_f32_e32 v94, 1.0, v94
	v_max_f32_e32 v13, 0, v13
	v_rcp_f32_e32 v94, v94
	v_sqrt_f32_e32 v108, v13
	v_add_f32_e32 v92, v170, v101
	v_mul_f32_e32 v92, 0xbfb8aa3b, v92
	v_exp_f32_e32 v92, v92
	v_pk_mul_f32 v[96:97], v[94:95], v[108:109]
	v_exp_f32_e32 v94, v86
	v_fmac_f32_e32 v97, v96, v140
	v_exp_f32_e32 v96, v87
	v_add_f32_e32 v92, 1.0, v92
	v_fma_f32 v86, -v94, v94, 1.0
	v_max_f32_e32 v86, 0, v86
	v_fma_f32 v87, -v96, v96, 1.0
	v_max_f32_e32 v87, 0, v87
	v_sqrt_f32_e32 v86, v86
	v_sqrt_f32_e32 v87, v87
	v_rcp_f32_e32 v92, v92
	v_mov_b32_e32 v99, v97
	v_pk_mul_f32 v[82:83], v[82:83], v[86:87]
	s_nop 0
	v_pk_mul_f32 v[82:83], v[82:83], v[6:7]
	v_add_f32_e32 v6, v171, v88
	v_mul_f32_e32 v6, 0xbfb8aa3b, v6
	v_exp_f32_e32 v6, v6
	v_add_f32_e32 v7, v173, v84
	v_mul_f32_e32 v7, 0xbfb8aa3b, v7
	v_exp_f32_e32 v7, v7
	v_add_f32_e32 v6, 1.0, v6
	v_rcp_f32_e32 v6, v6
	v_mul_f32_e32 v92, v174, v92
	v_add_f32_e32 v7, 1.0, v7
	v_rcp_f32_e32 v84, v7
	v_mul_f32_e32 v6, v175, v6
	v_exp_f32_e32 v7, v6
	v_add_f32_e32 v6, v171, v89
	v_mul_f32_e32 v6, 0xbfb8aa3b, v6
	v_exp_f32_e32 v6, v6
	v_exp_f32_e32 v101, v92
	v_rcp_f32_e32 v88, v85
	v_fma_f32 v85, v96, v82, v83
	v_add_f32_e32 v6, 1.0, v6
	v_rcp_f32_e32 v6, v6
	v_fma_f32 v13, -v101, v101, 1.0
	v_max_f32_e32 v13, 0, v13
	v_sqrt_f32_e32 v100, v13
	v_mul_f32_e32 v6, v175, v6
	v_exp_f32_e32 v197, v6
	v_fma_f32 v6, -v7, v7, 1.0
	v_max_f32_e32 v6, 0, v6
	v_sqrt_f32_e32 v6, v6
	v_mul_f32_e32 v13, v91, v11
	v_mul_f32_e32 v83, v96, v94
	v_pk_mul_f32 v[98:99], v[98:99], v[100:101]
	v_pk_mul_f32 v[86:87], v[84:85], v[6:7]
	v_fma_f32 v6, -v197, v197, 1.0
	v_max_f32_e32 v6, 0, v6
	v_sqrt_f32_e32 v196, v6
	v_fmac_f32_e32 v87, v86, v8
	v_mov_b32_e32 v89, v87
	v_mul_f32_e32 v91, v109, v13
	v_pk_mul_f32 v[88:89], v[88:89], v[196:197]
	v_mul_f32_e32 v84, v7, v83
	v_fmac_f32_e32 v99, v98, v141
	v_mul_f32_e32 v92, v101, v91
	v_fmac_f32_e32 v89, v88, v9
	v_mul_f32_e32 v86, v197, v84
	ds_bpermute_b32 v138, v0, v92
	ds_bpermute_b32 v140, v0, v99
	ds_bpermute_b32 v139, v0, v86
	ds_bpermute_b32 v141, v0, v89
	ds_bpermute_b32 v188, v0, v92 offset:64
	ds_bpermute_b32 v190, v0, v99 offset:64
	ds_bpermute_b32 v189, v0, v86 offset:64
	ds_bpermute_b32 v191, v0, v89 offset:64
	ds_bpermute_b32 v192, v0, v92 offset:128
	ds_bpermute_b32 v194, v0, v99 offset:128
	ds_bpermute_b32 v193, v0, v86 offset:128
	ds_bpermute_b32 v195, v0, v89 offset:128
	s_waitcnt lgkmcnt(8)
; __device__ __forceinline__ float fsig2(float x) { return __builtin_amdgcn_rcpf(1.0f + __builtin_amdgcn_exp2f(-LOG2E * x)); }
; template <int PASS> __device__ __forceinline__ void lru_wave_item(LAS unsigned char* lds, LAS unsigned char* vw, int b, int c, int h, const MixP& p, int lane, float (&Hrun)[8], bool cont) {
;     ...
;         for (int n = 0; n < 8; ++n) {
;             const f32x4 aVn = __builtin_amdgcn_mfma_f32_16x16x32_bf16(af[n >> 1], idf[n & 1], (f32x4){0.f, 0.f, 0.f, 0.f}, 0, 0, 0);
;             float av[4], bxv[4];
; #pragma unroll
;             for (int j = 0; j < 4; ++j) {
;                 const float r = fsig2(aR[n][j] + pba[n]), ig = fsig2(aI[n][j] + pbx[n]);
;                 const float a = __builtin_amdgcn_exp2f(r * pk8[n]), mult = __builtin_amdgcn_sqrtf(fmaxf(1.0f - a * a, 0.f));
;                 av[j] = a; bxv[j] = mult * ig * aVn[j];
;             }
;             const float H0 = bxv[0], H1 = av[1] * H0 + bxv[1], H2 = av[2] * H1 + bxv[2], H3 = av[3] * H2 + bxv[3];
;             const float A0 = av[0], A1 = av[1] * A0, A2 = av[2] * A1, A3 = av[3] * A2;
;             float At[4], Ht[4];
; #pragma unroll
;             for (int q = 0; q < 4; ++q) { At[q] = __shfl(A3, fr + 16 * q); Ht[q] = __shfl(H3, fr + 16 * q); }
;             const float c0 = Hrun[n], c1 = At[0] * c0 + Ht[0], c2 = At[1] * c1 + Ht[1], c3 = At[2] * c2 + Ht[2], c4 = At[3] * c3 + Ht[3];
;             Hrun[n] = c4;
;             if (PASS == 1) Arun[n] *= (At[0] * At[1]) * (At[2] * At[3]);
;             if (PASS == 2) {
;                 const float cin = fq == 0 ? c0 : (fq == 1 ? c1 : (fq == 2 ? c2 : c3));
;                 aR[n][0] = H0 + A0 * cin; aR[n][1] = H1 + A1 * cin; aR[n][2] = H2 + A2 * cin; aR[n][3] = H3 + A3 * cin;
;             }
;         }
	v_pk_fma_f32 v[8:9], v[14:15], v[138:139], v[140:141]
	ds_bpermute_b32 v108, v0, v99 offset:192
	s_waitcnt lgkmcnt(5)
	v_pk_fma_f32 v[138:139], v[8:9], v[188:189], v[190:191]
	ds_bpermute_b32 v109, v0, v89 offset:192
	s_waitcnt lgkmcnt(2)
	v_pk_fma_f32 v[6:7], v[138:139], v[192:193], v[194:195]
	ds_bpermute_b32 v100, v0, v92 offset:192
	v_cndmask_b32_e64 v88, v6, v138, s[8:9]
	v_cndmask_b32_e64 v8, v88, v8, s[6:7]
	v_cndmask_b32_e64 v8, v8, v14, s[4:5]
	v_fmac_f32_e32 v12, v11, v8
	v_fmac_f32_e32 v95, v13, v8
	v_fmac_f32_e32 v97, v91, v8
	v_fmac_f32_e32 v99, v92, v8
	v_cndmask_b32_e64 v8, v7, v139, s[8:9]
	v_cndmask_b32_e64 v8, v8, v9, s[6:7]
	v_cndmask_b32_e64 v8, v8, v15, s[4:5]
	v_fmac_f32_e32 v82, v94, v8
	v_fmac_f32_e32 v85, v83, v8
	v_fmac_f32_e32 v87, v84, v8
	v_fmac_f32_e32 v89, v86, v8
	v_add_f32_e32 v8, v176, v78
	v_mul_f32_e32 v8, 0xbfb8aa3b, v8
	v_exp_f32_e32 v8, v8
	v_mfma_f32_16x16x32_bf16 v[138:141], v[2:5], v[18:21], 0
	ds_bpermute_b32 v101, v0, v86 offset:192
	v_add_f32_e32 v8, 1.0, v8
	v_rcp_f32_e32 v9, v8
	v_add_f32_e32 v8, v178, v74
	v_mul_f32_e32 v8, 0xbfb8aa3b, v8
	v_exp_f32_e32 v8, v8
	v_mul_f32_e32 v9, v180, v9
	v_exp_f32_e32 v11, v9
	v_mfma_f32_16x16x32_bf16 v[2:5], v[2:5], v[22:25], 0
	v_add_f32_e32 v8, 1.0, v8
	v_rcp_f32_e32 v8, v8
	v_fma_f32 v9, -v11, v11, 1.0
	v_max_f32_e32 v9, 0, v9
	v_sqrt_f32_e32 v14, v9
	v_add_f32_e32 v9, v176, v79
	v_mul_f32_e32 v9, 0xbfb8aa3b, v9
	v_exp_f32_e32 v9, v9
	s_waitcnt lgkmcnt(0)
	v_pk_fma_f32 v[6:7], v[6:7], v[100:101], v[108:109]
	v_add_f32_e32 v9, 1.0, v9
	v_rcp_f32_e32 v13, v9
	v_add_f32_e32 v9, v178, v75
	v_mul_f32_e32 v9, 0xbfb8aa3b, v9
	v_exp_f32_e32 v9, v9
	v_mul_f32_e32 v13, v180, v13
	v_exp_f32_e32 v13, v13
	v_add_f32_e32 v75, v178, v77
	v_add_f32_e32 v9, 1.0, v9
	v_rcp_f32_e32 v9, v9
	v_fma_f32 v15, -v13, v13, 1.0
	v_max_f32_e32 v15, 0, v15
	v_sqrt_f32_e32 v15, v15
	v_mul_f32_e32 v75, 0xbfb8aa3b, v75
	v_exp_f32_e32 v75, v75
	v_pk_mul_f32 v[8:9], v[8:9], v[14:15]
	s_nop 0
	v_pk_mul_f32 v[14:15], v[8:9], v[138:139]
	v_add_f32_e32 v8, v176, v80
	v_mul_f32_e32 v8, 0xbfb8aa3b, v8
	v_exp_f32_e32 v8, v8
	v_add_f32_e32 v9, v178, v76
	v_mul_f32_e32 v9, 0xbfb8aa3b, v9
	v_exp_f32_e32 v9, v9
	v_add_f32_e32 v8, 1.0, v8
	v_rcp_f32_e32 v8, v8
	v_add_f32_e32 v75, 1.0, v75
	v_add_f32_e32 v9, 1.0, v9
	v_rcp_f32_e32 v74, v9
	v_mul_f32_e32 v8, v180, v8
	v_exp_f32_e32 v9, v8
	v_add_f32_e32 v8, v176, v81
	v_mul_f32_e32 v8, 0xbfb8aa3b, v8
	v_exp_f32_e32 v8, v8
	v_rcp_f32_e32 v78, v75
	v_fma_f32 v75, v13, v14, v15
	v_mul_f32_e32 v13, v13, v11
	v_add_f32_e32 v8, 1.0, v8
	v_rcp_f32_e32 v8, v8
	v_mul_f32_e32 v15, v9, v13
	v_mul_f32_e32 v8, v180, v8
	v_exp_f32_e32 v81, v8
	v_fma_f32 v8, -v9, v9, 1.0
	v_max_f32_e32 v8, 0, v8
	v_sqrt_f32_e32 v8, v8
	s_nop 0
	v_pk_mul_f32 v[76:77], v[74:75], v[8:9]
	v_add_f32_e32 v9, v177, v70
	v_mul_f32_e32 v9, 0xbfb8aa3b, v9
	v_exp_f32_e32 v9, v9
	v_fmac_f32_e32 v77, v76, v140
	v_fma_f32 v8, -v81, v81, 1.0
	v_max_f32_e32 v8, 0, v8
	v_add_f32_e32 v9, 1.0, v9
	v_rcp_f32_e32 v9, v9
	v_sqrt_f32_e32 v80, v8
	v_mov_b32_e32 v79, v77
	v_mul_f32_e32 v74, v81, v15
	v_mul_f32_e32 v9, v181, v9
	v_exp_f32_e32 v76, v9
	v_pk_mul_f32 v[78:79], v[78:79], v[80:81]
	ds_bpermute_b32 v8, v0, v74
	v_fmac_f32_e32 v79, v78, v141
	v_fma_f32 v9, -v76, v76, 1.0
	v_max_f32_e32 v9, 0, v9
	v_sqrt_f32_e32 v70, v9
	v_add_f32_e32 v9, v177, v71
	v_mul_f32_e32 v9, 0xbfb8aa3b, v9
	v_exp_f32_e32 v9, v9
	ds_bpermute_b32 v80, v0, v79
	ds_bpermute_b32 v138, v0, v74 offset:64
	ds_bpermute_b32 v140, v0, v79 offset:64
	v_add_f32_e32 v9, 1.0, v9
	v_rcp_f32_e32 v9, v9
	ds_bpermute_b32 v188, v0, v74 offset:128
	ds_bpermute_b32 v190, v0, v79 offset:128
	ds_bpermute_b32 v192, v0, v74 offset:192
	v_mul_f32_e32 v9, v181, v9
	v_exp_f32_e32 v9, v9
	ds_bpermute_b32 v194, v0, v79 offset:192
	v_fma_f32 v71, -v9, v9, 1.0
	v_max_f32_e32 v71, 0, v71
	v_sqrt_f32_e32 v71, v71
	s_nop 0
	v_pk_mul_f32 v[66:67], v[66:67], v[70:71]
	s_nop 0
	v_pk_mul_f32 v[66:67], v[66:67], v[2:3]
	v_add_f32_e32 v2, v177, v72
	v_mul_f32_e32 v2, 0xbfb8aa3b, v2
	v_exp_f32_e32 v2, v2
	v_add_f32_e32 v3, v179, v68
	v_mul_f32_e32 v3, 0xbfb8aa3b, v3
	v_exp_f32_e32 v3, v3
	v_add_f32_e32 v2, 1.0, v2
	v_rcp_f32_e32 v2, v2
	v_rcp_f32_e32 v70, v69
	v_add_f32_e32 v3, 1.0, v3
	v_rcp_f32_e32 v68, v3
	v_mul_f32_e32 v2, v181, v2
	v_exp_f32_e32 v3, v2
	v_add_f32_e32 v2, v177, v73
	v_mul_f32_e32 v2, 0xbfb8aa3b, v2
	v_exp_f32_e32 v2, v2
	v_fma_f32 v69, v9, v66, v67
	v_mul_f32_e32 v67, v9, v76
	v_add_f32_e32 v2, 1.0, v2
	v_rcp_f32_e32 v2, v2
	s_nop 0
	v_mul_f32_e32 v2, v181, v2
	v_exp_f32_e32 v73, v2
	v_fma_f32 v2, -v3, v3, 1.0
	v_max_f32_e32 v2, 0, v2
	v_sqrt_f32_e32 v2, v2
	s_nop 0
	v_pk_mul_f32 v[196:197], v[68:69], v[2:3]
	v_fma_f32 v2, -v73, v73, 1.0
	v_max_f32_e32 v2, 0, v2
	v_sqrt_f32_e32 v72, v2
	v_fmac_f32_e32 v197, v196, v4
	v_mov_b32_e32 v71, v197
	v_mul_f32_e32 v68, v3, v67
	v_pk_mul_f32 v[70:71], v[70:71], v[72:73]
	v_pk_fma_f32 v[2:3], v[126:127], v[184:185], v[186:187]
	v_fmac_f32_e32 v71, v70, v5
	v_mul_f32_e32 v70, v73, v68
	ds_bpermute_b32 v9, v0, v70
	ds_bpermute_b32 v81, v0, v71
	ds_bpermute_b32 v139, v0, v70 offset:64
	ds_bpermute_b32 v141, v0, v71 offset:64
	ds_bpermute_b32 v189, v0, v70 offset:128
	ds_bpermute_b32 v191, v0, v71 offset:128
	s_waitcnt lgkmcnt(4)
	v_pk_fma_f32 v[72:73], v[16:17], v[8:9], v[80:81]
	ds_bpermute_b32 v193, v0, v70 offset:192
	s_waitcnt lgkmcnt(3)
	v_pk_fma_f32 v[80:81], v[72:73], v[138:139], v[140:141]
	ds_bpermute_b32 v195, v0, v71 offset:192
	s_waitcnt lgkmcnt(2)
; #define LAS __attribute__((address_space(3)))
; __device__ __forceinline__ unsigned cvt_pk_bf16(float lo, float hi) { unsigned r; asm volatile("v_cvt_pk_bf16_f32 %0, %1, %2" : "=v"(r) : "v"(lo), "v"(hi)); return r; }
; __device__ __forceinline__ float bflo(unsigned w) { return __uint_as_float(w << 16); }
; __device__ __forceinline__ float bfhi(unsigned w) { return __uint_as_float(w & 0xffff0000u); }
; __device__ __forceinline__ u32x4 pack8(const f32x4 a, const f32x4 b) { u32x4 w; w.x = cvt_pk_bf16(a[0], a[1]); w.y = cvt_pk_bf16(a[2], a[3]); w.z = cvt_pk_bf16(b[0], b[1]); w.w = cvt_pk_bf16(b[2], b[3]); return w; }
; template <int PASS> __device__ __forceinline__ void lru_wave_item(LAS unsigned char* lds, LAS unsigned char* vw, int b, int c, int h, const MixP& p, int lane, float (&Hrun)[8], bool cont) {
;     ...
;                 const float cin = fq == 0 ? c0 : (fq == 1 ? c1 : (fq == 2 ? c2 : c3));
;                 aR[n][0] = H0 + A0 * cin; aR[n][1] = H1 + A1 * cin; aR[n][2] = H2 + A2 * cin; aR[n][3] = H3 + A3 * cin;
;             }
;         }
;         if (PASS == 2) {
; #pragma unroll
;             for (int n = 0; n < 8; ++n)
; #pragma unroll
;                 for (int j = 0; j < 4; j += 2) { const unsigned w = cvt_pk_bf16(aR[n][j], aR[n][j + 1]);
;                     *(LAS unsigned short*)(vw + (4 * fq + j) * WROW + (16 * n + fr) * 2) = (unsigned short)(w & 0xffffu);
;                     *(LAS unsigned short*)(vw + (4 * fq + j + 1) * WROW + (16 * n + fr) * 2) = (unsigned short)(w >> 16); }
; #pragma unroll
;             for (int i = 0; i < 4; ++i) {
;                 const int t = fq + 4 * i; const size_t row = (size_t)(row0 + 16 * st + t);
;                 const u32x4 hh = *(const LAS u32x4*)(vw + t * WROW + cg * 16);
;                 const u32x4 g = *(const u32x4*)(p.P2 + row * P2W + h * 128 + cg * 8);
;                 const f32x4 o0 = (f32x4){bflo(hh.x) * bflo(g.x), bfhi(hh.x) * bfhi(g.x), bflo(hh.y) * bflo(g.y), bfhi(hh.y) * bfhi(g.y)};
;                 const f32x4 o1 = (f32x4){bflo(hh.z) * bflo(g.z), bfhi(hh.z) * bfhi(g.z), bflo(hh.w) * bflo(g.w), bfhi(hh.w) * bfhi(g.w)};
;                 *(u32x4*)(p.hl + row * LW + h * 128 + cg * 8) = pack8(o0, o1);
;             }
	v_pk_fma_f32 v[138:139], v[80:81], v[188:189], v[190:191]
	v_pk_fma_f32 v[4:5], v[106:107], v[116:117], v[128:129]
	v_cndmask_b32_e64 v0, v138, v80, s[8:9]
	v_cndmask_b32_e64 v0, v0, v72, s[6:7]
	v_cndmask_b32_e64 v0, v0, v16, s[4:5]
	v_fmac_f32_e32 v14, v11, v0
	v_fmac_f32_e32 v75, v13, v0
	v_fmac_f32_e32 v77, v15, v0
	v_fmac_f32_e32 v79, v74, v0
	v_cndmask_b32_e64 v0, v139, v81, s[8:9]
	v_cndmask_b32_e64 v0, v0, v73, s[6:7]
	v_cndmask_b32_e64 v0, v0, v17, s[4:5]
	v_fmac_f32_e32 v66, v76, v0
	v_fmac_f32_e32 v69, v67, v0
	v_fmac_f32_e32 v197, v68, v0
	v_fmac_f32_e32 v71, v70, v0
	v_cvt_pk_bf16_f32 v0, v130, v133
	ds_write_b16 v234, v0
	ds_write_b16_d16_hi v234, v0 offset:272
	v_cvt_pk_bf16_f32 v0, v135, v137
	ds_write_b16 v234, v0 offset:544
	ds_write_b16_d16_hi v234, v0 offset:816
	v_cvt_pk_bf16_f32 v0, v118, v121
	ds_write_b16 v234, v0 offset:32
	ds_write_b16_d16_hi v234, v0 offset:304
	v_cvt_pk_bf16_f32 v0, v123, v125
	ds_write_b16 v234, v0 offset:576
	ds_write_b16_d16_hi v234, v0 offset:848
	v_cvt_pk_bf16_f32 v0, v10, v111
	ds_write_b16 v234, v0 offset:64
	ds_write_b16_d16_hi v234, v0 offset:336
	v_cvt_pk_bf16_f32 v0, v113, v115
	ds_write_b16 v234, v0 offset:608
	ds_write_b16_d16_hi v234, v0 offset:880
	v_cvt_pk_bf16_f32 v0, v90, v93
	ds_write_b16 v234, v0 offset:96
	ds_write_b16_d16_hi v234, v0 offset:368
	v_cvt_pk_bf16_f32 v0, v103, v105
	ds_write_b16 v234, v0 offset:640
	ds_write_b16_d16_hi v234, v0 offset:912
	v_cvt_pk_bf16_f32 v0, v12, v95
	ds_write_b16 v234, v0 offset:128
	ds_write_b16_d16_hi v234, v0 offset:400
	v_cvt_pk_bf16_f32 v0, v97, v99
	ds_write_b16 v234, v0 offset:672
	ds_write_b16_d16_hi v234, v0 offset:944
	v_cvt_pk_bf16_f32 v0, v82, v85
	ds_write_b16 v234, v0 offset:160
	ds_write_b16_d16_hi v234, v0 offset:432
	v_cvt_pk_bf16_f32 v0, v87, v89
	ds_write_b16 v234, v0 offset:704
	ds_write_b16_d16_hi v234, v0 offset:976
	v_cvt_pk_bf16_f32 v0, v14, v75
	ds_write_b16 v234, v0 offset:192
	ds_write_b16_d16_hi v234, v0 offset:464
	v_cvt_pk_bf16_f32 v0, v77, v79
	ds_write_b16 v234, v0 offset:736
	ds_write_b16_d16_hi v234, v0 offset:1008
	v_cvt_pk_bf16_f32 v0, v66, v69
	ds_write_b16 v234, v0 offset:224
	ds_write_b16_d16_hi v234, v0 offset:496
	v_cvt_pk_bf16_f32 v0, v197, v71
	ds_write_b16 v234, v0 offset:768
	ds_write_b16_d16_hi v234, v0 offset:1040
	v_or_b32_e32 v0, s19, v203
	ds_read_b128 v[10:13], v235
	s_waitcnt lgkmcnt(14)
	v_pk_fma_f32 v[8:9], v[138:139], v[192:193], v[194:195]
	s_waitcnt lgkmcnt(0)
	v_lshlrev_b32_e32 v67, 16, v10
	v_and_b32_e32 v10, 0xffff0000, v10
	s_waitcnt vmcnt(11)
	v_lshlrev_b32_e32 v66, 16, v240
	v_and_b32_e32 v240, 0xffff0000, v240
	v_mul_f32_e32 v66, v66, v67
	v_mul_f32_e32 v10, v240, v10
	v_lshlrev_b32_e32 v240, 16, v241
	v_lshlrev_b32_e32 v67, 16, v11
	v_and_b32_e32 v241, 0xffff0000, v241
	v_and_b32_e32 v11, 0xffff0000, v11
	v_mul_f32_e32 v240, v240, v67
	v_mul_f32_e32 v11, v241, v11
	v_lshlrev_b32_e32 v241, 16, v242
	v_lshlrev_b32_e32 v67, 16, v12
	v_and_b32_e32 v242, 0xffff0000, v242
	v_and_b32_e32 v12, 0xffff0000, v12
	v_mul_f32_e32 v241, v241, v67
	v_mul_f32_e32 v12, v242, v12
	v_lshlrev_b32_e32 v242, 16, v243
	v_lshlrev_b32_e32 v67, 16, v13
	v_and_b32_e32 v243, 0xffff0000, v243
	v_and_b32_e32 v13, 0xffff0000, v13
	v_mul_f32_e32 v13, v243, v13
	v_cvt_pk_bf16_f32 v10, v66, v10
	v_cvt_pk_bf16_f32 v11, v240, v11
	v_cvt_pk_bf16_f32 v12, v241, v12
	v_mad_i64_i32 v[14:15], s[20:21], v0, s40, v[154:155]
	v_or_b32_e32 v0, s19, v225
	v_mul_f32_e32 v242, v242, v67
	v_cvt_pk_bf16_f32 v13, v242, v13
	global_store_dwordx4 v[14:15], v[10:13], off sc1
	ds_read_b128 v[10:13], v235 offset:1088
	s_waitcnt lgkmcnt(0)
; #define LAS __attribute__((address_space(3)))
; __device__ __forceinline__ float bflo(unsigned w) { return __uint_as_float(w << 16); }
; __device__ __forceinline__ float bfhi(unsigned w) { return __uint_as_float(w & 0xffff0000u); }
; __device__ __forceinline__ u32x4 pack8(const f32x4 a, const f32x4 b) { u32x4 w; w.x = cvt_pk_bf16(a[0], a[1]); w.y = cvt_pk_bf16(a[2], a[3]); w.z = cvt_pk_bf16(b[0], b[1]); w.w = cvt_pk_bf16(b[2], b[3]); return w; }
; template <int PASS> __device__ __forceinline__ void lru_wave_item(LAS unsigned char* lds, LAS unsigned char* vw, int b, int c, int h, const MixP& p, int lane, float (&Hrun)[8], bool cont) {
;     ...
;             for (int i = 0; i < 4; ++i) {
;                 const int t = fq + 4 * i; const size_t row = (size_t)(row0 + 16 * st + t);
;                 const u32x4 hh = *(const LAS u32x4*)(vw + t * WROW + cg * 16);
;                 const u32x4 g = *(const u32x4*)(p.P2 + row * P2W + h * 128 + cg * 8);
;                 const f32x4 o0 = (f32x4){bflo(hh.x) * bflo(g.x), bfhi(hh.x) * bfhi(g.x), bflo(hh.y) * bflo(g.y), bfhi(hh.y) * bfhi(g.y)};
;                 const f32x4 o1 = (f32x4){bflo(hh.z) * bflo(g.z), bfhi(hh.z) * bfhi(g.z), bflo(hh.w) * bflo(g.w), bfhi(hh.w) * bfhi(g.w)};
;                 *(u32x4*)(p.hl + row * LW + h * 128 + cg * 8) = pack8(o0, o1);
;             }
	v_lshlrev_b32_e32 v66, 16, v10
	v_and_b32_e32 v10, 0xffff0000, v10
	s_waitcnt vmcnt(11)
	v_lshlrev_b32_e32 v67, 16, v244
	v_and_b32_e32 v244, 0xffff0000, v244
	v_mul_f32_e32 v66, v67, v66
	v_mul_f32_e32 v10, v244, v10
	v_lshlrev_b32_e32 v244, 16, v11
	v_lshlrev_b32_e32 v67, 16, v245
	v_and_b32_e32 v245, 0xffff0000, v245
	v_and_b32_e32 v11, 0xffff0000, v11
	v_mul_f32_e32 v244, v67, v244
	v_mul_f32_e32 v11, v245, v11
	v_lshlrev_b32_e32 v245, 16, v12
	v_lshlrev_b32_e32 v67, 16, v246
	v_and_b32_e32 v246, 0xffff0000, v246
	v_and_b32_e32 v12, 0xffff0000, v12
	v_mul_f32_e32 v245, v67, v245
	v_mul_f32_e32 v12, v246, v12
	v_lshlrev_b32_e32 v246, 16, v13
	v_lshlrev_b32_e32 v67, 16, v247
	v_and_b32_e32 v247, 0xffff0000, v247
	v_and_b32_e32 v13, 0xffff0000, v13
	v_mul_f32_e32 v13, v247, v13
	v_cvt_pk_bf16_f32 v10, v66, v10
	v_cvt_pk_bf16_f32 v11, v244, v11
	v_cvt_pk_bf16_f32 v12, v245, v12
	v_mad_i64_i32 v[14:15], s[20:21], v0, s40, v[154:155]
	v_or_b32_e32 v0, s19, v226
	v_mul_f32_e32 v246, v67, v246
	v_cvt_pk_bf16_f32 v13, v246, v13
	global_store_dwordx4 v[14:15], v[10:13], off sc1
	ds_read_b128 v[10:13], v235 offset:2176
	s_waitcnt lgkmcnt(0)
	v_lshlrev_b32_e32 v66, 16, v10
	v_and_b32_e32 v10, 0xffff0000, v10
	s_waitcnt vmcnt(11)
	v_lshlrev_b32_e32 v67, 16, v248
	v_and_b32_e32 v248, 0xffff0000, v248
	v_mul_f32_e32 v66, v67, v66
	v_mul_f32_e32 v10, v248, v10
	v_lshlrev_b32_e32 v248, 16, v11
	v_lshlrev_b32_e32 v67, 16, v249
	v_and_b32_e32 v249, 0xffff0000, v249
	v_and_b32_e32 v11, 0xffff0000, v11
	v_mul_f32_e32 v248, v67, v248
	v_mul_f32_e32 v11, v249, v11
	v_lshlrev_b32_e32 v249, 16, v12
	v_lshlrev_b32_e32 v67, 16, v250
	v_and_b32_e32 v250, 0xffff0000, v250
	v_and_b32_e32 v12, 0xffff0000, v12
	v_mul_f32_e32 v249, v67, v249
	v_mul_f32_e32 v12, v250, v12
	v_lshlrev_b32_e32 v250, 16, v13
	v_lshlrev_b32_e32 v67, 16, v251
	v_and_b32_e32 v251, 0xffff0000, v251
	v_and_b32_e32 v13, 0xffff0000, v13
	v_mul_f32_e32 v13, v251, v13
	v_cvt_pk_bf16_f32 v10, v66, v10
	v_cvt_pk_bf16_f32 v11, v248, v11
	v_cvt_pk_bf16_f32 v12, v249, v12
	v_mad_i64_i32 v[14:15], s[20:21], v0, s40, v[154:155]
	v_or_b32_e32 v0, s19, v227
	v_mul_f32_e32 v250, v67, v250
	v_cvt_pk_bf16_f32 v13, v250, v13
	global_store_dwordx4 v[14:15], v[10:13], off sc1
	ds_read_b128 v[10:13], v235 offset:3264
	s_mov_b32 s19, 16
	s_waitcnt lgkmcnt(0)
	v_lshlrev_b32_e32 v66, 16, v10
	v_and_b32_e32 v10, 0xffff0000, v10
	s_waitcnt vmcnt(10)
	v_lshlrev_b32_e32 v67, 16, v206
	v_and_b32_e32 v206, 0xffff0000, v206
	v_mul_f32_e32 v66, v67, v66
	v_mul_f32_e32 v10, v206, v10
	v_lshlrev_b32_e32 v206, 16, v11
	v_lshlrev_b32_e32 v67, 16, v207
	v_and_b32_e32 v207, 0xffff0000, v207
	v_and_b32_e32 v11, 0xffff0000, v11
	v_mul_f32_e32 v206, v67, v206
	v_mul_f32_e32 v11, v207, v11
	v_lshlrev_b32_e32 v207, 16, v12
	v_lshlrev_b32_e32 v67, 16, v210
	v_and_b32_e32 v210, 0xffff0000, v210
	v_and_b32_e32 v12, 0xffff0000, v12
	v_mul_f32_e32 v207, v67, v207
	v_mul_f32_e32 v12, v210, v12
	v_lshlrev_b32_e32 v210, 16, v13
	v_lshlrev_b32_e32 v67, 16, v211
	v_and_b32_e32 v211, 0xffff0000, v211
	v_and_b32_e32 v13, 0xffff0000, v13
	v_mul_f32_e32 v13, v211, v13
	v_mul_f32_e32 v210, v67, v210
	v_cvt_pk_bf16_f32 v10, v66, v10
	v_cvt_pk_bf16_f32 v11, v206, v11
	v_cvt_pk_bf16_f32 v12, v207, v12
	v_cvt_pk_bf16_f32 v13, v210, v13
	v_mad_i64_i32 v[14:15], s[20:21], v0, s40, v[154:155]
	global_store_dwordx4 v[14:15], v[10:13], off sc1
	v_mov_b64_e32 v[16:17], v[8:9]
	v_mov_b64_e32 v[14:15], v[6:7]
	v_mov_b64_e32 v[12:13], v[4:5]
	v_mov_b64_e32 v[10:11], v[2:3]
	s_cbranch_vccnz .LBB0_818
	s_add_i32 s1, s1, 1
	s_cmp_ge_i32 s1, s10
	s_cbranch_scc0 .LBB0_811
	s_branch .LBB0_797
